# attention item body rewritten by hand: 32-key sub-tile ping-pong pipeline, 3 LDS buffers, pipelined last tile, early epilogue loads, max folded into MFMA C operand, scalar work-list fetch
# speedup vs baseline: 1.0550x; 1.0280x over previous
.LBB0_469:
	s_or_b64 exec, exec, s[6:7]
	s_add_u32 s4, s38, 0x6000000
	s_addc_u32 s5, s39, 0
	s_mov_b32 s43, 0
	s_add_u32 s40, s38, 0x6500000
	s_mov_b32 s3, s43
	s_addc_u32 s41, s39, 0
	s_lshl_b64 s[6:7], s[2:3], 3
	s_add_u32 s3, s0, s6
	s_addc_u32 s67, s1, s7
	s_mov_b32 s6, s3
	s_mov_b32 s7, s67
	s_load_dwordx2 s[100:101], s[6:7], 0xa0
	s_cmpk_lg_i32 s33, 0x100
	s_cselect_b64 s[44:45], -1, 0
	s_add_u32 s46, s38, 0x2080000
	s_addc_u32 s47, s39, 0
	s_add_u32 s48, s38, 0x57c0000
	s_addc_u32 s49, s39, 0
	s_add_u32 s50, s38, 0x67a8000
	s_addc_u32 s51, s39, 0
	s_add_u32 s52, s38, 0x77e8000
	s_movk_i32 s68, 0x100
	s_addc_u32 s53, s39, 0
	v_mov_b32_e32 v1, 0
	s_movk_i32 s69, 0xa00
	s_movk_i32 s70, 0xa0
	s_movk_i32 s71, 0x140
	s_mov_b64 s[54:55], 0x2800
	s_movk_i32 s72, 0x2000
	s_mov_b64 s[56:57], 0x100
	s_movk_i32 s73, 0x800
	s_mov_b64 s[58:59], 0x5100
	s_mov_b64 s[60:61], 0x5000
	s_movk_i32 s74, 0x1000
	s_movk_i32 s75, 0x3000
	v_mov_b32_e32 v164, 0xf149f2ca
	v_mbcnt_hi_u32_b32 v197, -1, v214
	s_mov_b32 s42, s43
	s_barrier
	s_branch .LBB0_472

.LBB0_474:
	s_andn2_b64 vcc, exec, s[8:9]
	s_cbranch_vccnz .LBB0_477
	s_cmp_lt_u32 s42, 4
	s_cbranch_scc0 .LBB0_477
	s_waitcnt lgkmcnt(0)
	s_lshl_b32 s6, s42, 4
	s_lshr_b64 s[6:7], s[100:101], s6
	s_sext_i32_i16 s14, s6
	s_cmp_gt_i32 s14, -1
	s_cselect_b64 s[6:7], -1, 0


.LBB0_485:
	s_or_b64 exec, exec, s[12:13]
	v_lshrrev_b32_e32 v8, 3, v165
	v_and_b32_e32 v8, 2, v8
	v_bfe_u32 v9, v165, 1, 1
	v_bfe_u32 v7, v165, 2, 2
	v_or_b32_e32 v10, v8, v9
	v_lshlrev_b32_e32 v166, 2, v4
	v_lshlrev_b32_e32 v11, 3, v165
	v_and_b32_e32 v11, 8, v11
	v_or_b32_e32 v13, v166, v7
	v_bitop3_b32 v8, v8, v4, v9 bitop3:0x36
	v_bitop3_b32 v10, v4, v10, 2 bitop3:0x36
	v_lshlrev_b32_e32 v3, 2, v165
	v_lshlrev_b32_e32 v12, 6, v7
	v_lshlrev_b32_e32 v13, 8, v13
	v_lshlrev_b32_e32 v8, 4, v8
	v_lshl_or_b32 v10, v10, 4, v11
	s_waitcnt vmcnt(0)
	v_or3_b32 v8, v13, v8, v11
	v_xor_b32_e32 v9, 64, v12
	v_xor_b32_e32 v14, 0x80, v12
	v_xor_b32_e32 v15, 0xc0, v12
	v_or3_b32 v10, v13, v10, s73
	v_and_b32_e32 v3, 12, v3
	v_and_b32_e32 v167, 31, v165
	v_or_b32_e32 v155, v8, v12
	v_or_b32_e32 v168, v8, v9
	v_or_b32_e32 v169, v8, v14
	v_or_b32_e32 v170, v8, v15
	v_or_b32_e32 v8, 2, v4
	v_add_u32_e32 v172, v10, v9
	v_or_b32_e32 v9, v3, v7
	v_bitop3_b32 v3, v3, v4, v7 bitop3:0x36
	v_lshlrev_b32_e32 v184, 8, v167
	v_add_u32_e32 v171, v10, v12
	v_add_u32_e32 v173, v10, v14
	v_add_u32_e32 v174, v10, v15
	v_lshlrev_b32_e32 v176, 6, v167
	v_lshlrev_b32_e32 v189, 4, v3
	s_cmp_eq_u32 s15, 1
	v_xor_b32_e32 v188, v8, v9
	v_bitop3_b32 v187, v4, v9, 4 bitop3:0x36
	v_bitop3_b32 v186, v4, v9, 6 bitop3:0x36
	v_bitop3_b32 v185, v4, v9, 8 bitop3:0x36
	v_bitop3_b32 v182, v4, v9, 10 bitop3:0x36
	v_bitop3_b32 v180, v4, v9, 12 bitop3:0x36
	v_bitop3_b32 v179, v4, v9, 14 bitop3:0x36
	v_xor_b32_e32 v178, v4, v7
	v_xor_b32_e32 v177, v8, v7
	s_waitcnt vmcnt(0) lgkmcnt(0)
	s_barrier
	v_add_u32_e32 v190, v184, v189
	v_lshl_add_u32 v191, v188, 4, v184
	v_lshl_add_u32 v192, v187, 4, v184
	v_lshl_add_u32 v193, v186, 4, v184
	v_lshl_add_u32 v194, v185, 4, v184
	v_lshl_add_u32 v195, v182, 4, v184
	v_lshl_add_u32 v196, v180, 4, v184
	v_lshl_add_u32 v198, v179, 4, v184
	v_lshl_add_u32 v199, v178, 4, v176
	v_lshl_add_u32 v200, v177, 4, v176
	v_readfirstlane_b32 s16, v181
	s_add_i32 s12, s15, -1
	s_cmp_lg_u64 s[8:9], 0
	s_cselect_b32 s17, 16, 0xffff
	s_mov_b32 s13, 0
	v_lshl_add_u64 v[162:163], v[156:157], 0, s[60:61]
	v_lshl_add_u64 v[160:161], v[158:159], 0, s[58:59]
	s_cmp_eq_u32 s15, 1
	s_cbranch_scc1 .Lat3_onetile
	s_add_u32 m0, s16, 20480
	v_lshl_add_u64 v[202:203], v[162:163], 0, s[54:55]
	global_load_lds_dwordx4 v[162:163], off
	v_lshl_add_u64 v[162:163], v[162:163], 0, s[60:61]
	s_add_u32 m0, s16, 28672
	s_nop 0
	global_load_lds_dwordx4 v[202:203], off
	s_cmp_eq_u64 s[6:7], 0
	s_cbranch_scc1 .Lat3_norope_pre
	s_add_u32 m0, s16, 36864
	s_nop 0
	global_load_lds_dwordx4 v[160:161], off
	v_lshl_add_u64 v[160:161], v[160:161], 0, s[60:61]
.Lat3_norope_pre:
.Lat3_onetile:
	ds_read_b128 v[220:223], v190 offset:0
	ds_read_b128 v[224:227], v191 offset:0
	ds_read_b128 v[228:231], v192 offset:0
	s_waitcnt lgkmcnt(2)
	v_mfma_f32_32x32x16_bf16 v[96:111], v[220:223], v[148:151], 0
	ds_read_b128 v[220:223], v193 offset:0
	v_mov_b32_e32 v16, 0
	v_mov_b32_e32 v17, 0
	v_mov_b32_e32 v18, 0
	v_mov_b32_e32 v19, 0
	v_mov_b32_e32 v20, 0
	v_mov_b32_e32 v21, 0
	v_mov_b32_e32 v22, 0
	s_waitcnt lgkmcnt(2)
	v_mfma_f32_32x32x16_bf16 v[96:111], v[224:227], v[144:147], v[96:111]
	ds_read_b128 v[224:227], v194 offset:0
	v_mov_b32_e32 v23, 0
	v_mov_b32_e32 v24, 0
	v_mov_b32_e32 v25, 0
	v_mov_b32_e32 v26, 0
	v_mov_b32_e32 v27, 0
	v_mov_b32_e32 v28, 0
	v_mov_b32_e32 v29, 0
	s_waitcnt lgkmcnt(2)
	v_mfma_f32_32x32x16_bf16 v[96:111], v[228:231], v[140:143], v[96:111]
	ds_read_b128 v[228:231], v195 offset:0
	v_mov_b32_e32 v30, 0
	v_mov_b32_e32 v31, 0
	v_mov_b32_e32 v32, 0
	v_mov_b32_e32 v33, 0
	v_mov_b32_e32 v34, 0
	v_mov_b32_e32 v35, 0
	v_mov_b32_e32 v36, 0
	s_waitcnt lgkmcnt(2)
	v_mfma_f32_32x32x16_bf16 v[96:111], v[220:223], v[136:139], v[96:111]
	ds_read_b128 v[220:223], v196 offset:0
	v_mov_b32_e32 v37, 0
	v_mov_b32_e32 v38, 0
	v_mov_b32_e32 v39, 0
	v_mov_b32_e32 v40, 0
	v_mov_b32_e32 v41, 0
	v_mov_b32_e32 v42, 0
	v_mov_b32_e32 v43, 0
	s_waitcnt lgkmcnt(2)
	v_mfma_f32_32x32x16_bf16 v[96:111], v[224:227], v[132:135], v[96:111]
	ds_read_b128 v[224:227], v198 offset:0
	v_mov_b32_e32 v44, 0
	v_mov_b32_e32 v45, 0
	v_mov_b32_e32 v46, 0
	v_mov_b32_e32 v47, 0
	v_mov_b32_e32 v48, 0
	v_mov_b32_e32 v49, 0
	v_mov_b32_e32 v50, 0
	s_waitcnt lgkmcnt(2)
	v_mfma_f32_32x32x16_bf16 v[96:111], v[228:231], v[128:131], v[96:111]
	ds_read_b128 v[228:231], v199 offset:16384
	v_mov_b32_e32 v51, 0
	v_mov_b32_e32 v52, 0
	v_mov_b32_e32 v53, 0
	v_mov_b32_e32 v54, 0
	v_mov_b32_e32 v55, 0
	v_mov_b32_e32 v56, 0
	v_mov_b32_e32 v57, 0
	s_waitcnt lgkmcnt(2)
	v_mfma_f32_32x32x16_bf16 v[96:111], v[220:223], v[124:127], v[96:111]
	ds_read_b128 v[220:223], v200 offset:16384
	v_mov_b32_e32 v58, 0
	v_mov_b32_e32 v59, 0
	v_mov_b32_e32 v60, 0
	v_mov_b32_e32 v61, 0
	v_mov_b32_e32 v62, 0
	v_mov_b32_e32 v63, 0
	v_mov_b32_e32 v64, 0
	s_waitcnt lgkmcnt(2)
	v_mfma_f32_32x32x16_bf16 v[96:111], v[224:227], v[120:123], v[96:111]
	v_mov_b32_e32 v65, 0
	v_mov_b32_e32 v66, 0
	v_mov_b32_e32 v67, 0
	v_mov_b32_e32 v68, 0
	v_mov_b32_e32 v69, 0
	v_mov_b32_e32 v70, 0
	v_mov_b32_e32 v71, 0
	s_waitcnt lgkmcnt(1)
	v_mfma_f32_32x32x16_bf16 v[96:111], v[228:231], v[116:119], v[96:111]
	v_mov_b32_e32 v72, 0
	v_mov_b32_e32 v73, 0
	v_mov_b32_e32 v74, 0
	v_mov_b32_e32 v75, 0
	v_mov_b32_e32 v76, 0
	v_mov_b32_e32 v77, 0
	v_mov_b32_e32 v78, 0
	s_waitcnt lgkmcnt(0)
	v_mfma_f32_32x32x16_bf16 v[96:111], v[220:223], v[112:115], v[96:111]
	v_mov_b32_e32 v79, 0
	v_mov_b32_e32 v175, 0
	s_nop 12
	v_max3_f32 v14, v96, v97, v98
	v_max3_f32 v14, v14, v99, v100
	v_max3_f32 v14, v14, v101, v102
	v_max3_f32 v14, v14, v103, v104
	v_max3_f32 v14, v14, v105, v106
	v_max3_f32 v14, v14, v107, v108
	v_max3_f32 v14, v14, v109, v110
	v_max_f32_e32 v14, v14, v111
	v_mov_b32_e32 v15, v14
	s_nop 1
	v_permlane32_swap_b32_e32 v14, v15
	v_max_f32_e32 v14, v14, v15
	v_sub_f32_e32 v96, v96, v14
	v_sub_f32_e32 v97, v97, v14
	v_sub_f32_e32 v98, v98, v14
	v_sub_f32_e32 v99, v99, v14
	v_sub_f32_e32 v100, v100, v14
	v_sub_f32_e32 v101, v101, v14
	v_sub_f32_e32 v102, v102, v14
	v_sub_f32_e32 v103, v103, v14
	v_sub_f32_e32 v104, v104, v14
	v_sub_f32_e32 v105, v105, v14
	v_sub_f32_e32 v106, v106, v14
	v_sub_f32_e32 v107, v107, v14
	v_sub_f32_e32 v108, v108, v14
	v_sub_f32_e32 v109, v109, v14
	v_sub_f32_e32 v110, v110, v14
	v_sub_f32_e32 v111, v111, v14
	v_mul_f32_e32 v232, -1.0, v14
	v_mul_f32_e32 v233, -1.0, v14
	v_mul_f32_e32 v234, -1.0, v14
	v_mul_f32_e32 v235, -1.0, v14
	v_mul_f32_e32 v236, -1.0, v14
	v_mul_f32_e32 v237, -1.0, v14
	v_mul_f32_e32 v238, -1.0, v14
	v_mul_f32_e32 v239, -1.0, v14
	v_mul_f32_e32 v240, -1.0, v14
	v_mul_f32_e32 v241, -1.0, v14
	v_mul_f32_e32 v242, -1.0, v14
	v_mul_f32_e32 v243, -1.0, v14
	v_mul_f32_e32 v244, -1.0, v14
	v_mul_f32_e32 v245, -1.0, v14
	v_mul_f32_e32 v246, -1.0, v14
	v_mul_f32_e32 v247, -1.0, v14
.Lat3_a:
	s_cmp_eq_u32 s13, s17
	s_cbranch_scc1 .Lat3_smp_a
	ds_read_b128 v[220:223], v190 offset:8192
	ds_read_b128 v[224:227], v191 offset:8192
	ds_read_b128 v[228:231], v192 offset:8192
	v_exp_f32_e32 v96, v96
	v_exp_f32_e32 v97, v97
	v_exp_f32_e32 v98, v98
	v_exp_f32_e32 v99, v99
	s_waitcnt lgkmcnt(2)
	v_mfma_f32_32x32x16_bf16 v[80:95], v[220:223], v[148:151], v[232:247]
	ds_read_b128 v[220:223], v193 offset:8192
	v_exp_f32_e32 v100, v100
	v_exp_f32_e32 v101, v101
	s_waitcnt lgkmcnt(2)
	v_mfma_f32_32x32x16_bf16 v[80:95], v[224:227], v[144:147], v[80:95]
	ds_read_b128 v[224:227], v194 offset:8192
	v_cvt_pk_bf16_f32 v6, v96, v97
	v_exp_f32_e32 v102, v102
	s_waitcnt lgkmcnt(2)
	v_mfma_f32_32x32x16_bf16 v[80:95], v[228:231], v[140:143], v[80:95]
	ds_read_b128 v[228:231], v195 offset:8192
	v_exp_f32_e32 v103, v103
	v_cvt_pk_bf16_f32 v7, v98, v99
	s_waitcnt lgkmcnt(2)
	v_mfma_f32_32x32x16_bf16 v[80:95], v[220:223], v[136:139], v[80:95]
	ds_read_b128 v[220:223], v196 offset:8192
	v_cvt_pk_bf16_f32 v8, v100, v101
	v_exp_f32_e32 v104, v104
	s_waitcnt lgkmcnt(2)
	v_mfma_f32_32x32x16_bf16 v[80:95], v[224:227], v[132:135], v[80:95]
	ds_read_b128 v[224:227], v198 offset:8192
	v_exp_f32_e32 v105, v105
	v_cvt_pk_bf16_f32 v9, v102, v103
	s_waitcnt lgkmcnt(2)
	v_mfma_f32_32x32x16_bf16 v[80:95], v[228:231], v[128:131], v[80:95]
	ds_read_b128 v[228:231], v199 offset:18432
	v_exp_f32_e32 v106, v106
	v_exp_f32_e32 v107, v107
	s_waitcnt lgkmcnt(2)
	v_mfma_f32_32x32x16_bf16 v[80:95], v[220:223], v[124:127], v[80:95]
	ds_read_b128 v[220:223], v200 offset:18432
	v_cvt_pk_bf16_f32 v10, v104, v105
	v_exp_f32_e32 v108, v108
	s_waitcnt lgkmcnt(2)
	v_mfma_f32_32x32x16_bf16 v[80:95], v[224:227], v[120:123], v[80:95]
	ds_read_b64_tr_b16 v[204:205], v155 offset:0
	ds_read_b64_tr_b16 v[206:207], v171 offset:0
	v_exp_f32_e32 v109, v109
	v_cvt_pk_bf16_f32 v11, v106, v107
	s_waitcnt lgkmcnt(3)
	v_mfma_f32_32x32x16_bf16 v[80:95], v[228:231], v[116:119], v[80:95]
	ds_read_b64_tr_b16 v[208:209], v168 offset:0
	ds_read_b64_tr_b16 v[210:211], v172 offset:0
	v_exp_f32_e32 v110, v110
	v_exp_f32_e32 v111, v111
	s_waitcnt lgkmcnt(4)
	v_mfma_f32_32x32x16_bf16 v[80:95], v[220:223], v[112:115], v[80:95]
	ds_read_b64_tr_b16 v[176:177], v169 offset:0
	ds_read_b64_tr_b16 v[178:179], v173 offset:0
	v_cvt_pk_bf16_f32 v12, v108, v109
	v_cvt_pk_bf16_f32 v13, v110, v111
	s_waitcnt lgkmcnt(4)
	v_mfma_f32_32x32x16_bf16 v[64:79], v[204:207], v[6:9], v[64:79]
	ds_read_b64_tr_b16 v[184:185], v170 offset:0
	ds_read_b64_tr_b16 v[186:187], v174 offset:0
	v_add_f32_e32 v175, v175, v96
	v_add_f32_e32 v175, v175, v97
	v_add_f32_e32 v175, v175, v98
	v_add_f32_e32 v175, v175, v99
	s_waitcnt lgkmcnt(4)
	v_mfma_f32_32x32x16_bf16 v[48:63], v[208:211], v[6:9], v[48:63]
	ds_read_b64_tr_b16 v[204:205], v155 offset:4096
	ds_read_b64_tr_b16 v[206:207], v171 offset:4096
	v_add_f32_e32 v175, v175, v100
	v_add_f32_e32 v175, v175, v101
	v_add_f32_e32 v175, v175, v102
	v_add_f32_e32 v175, v175, v103
	s_waitcnt lgkmcnt(4)
	v_mfma_f32_32x32x16_bf16 v[32:47], v[176:179], v[6:9], v[32:47]
	ds_read_b64_tr_b16 v[208:209], v168 offset:4096
	ds_read_b64_tr_b16 v[210:211], v172 offset:4096
	v_add_f32_e32 v175, v175, v104
	v_add_f32_e32 v175, v175, v105
	v_add_f32_e32 v175, v175, v106
	v_add_f32_e32 v175, v175, v107
	s_waitcnt lgkmcnt(4)
	v_mfma_f32_32x32x16_bf16 v[16:31], v[184:187], v[6:9], v[16:31]
	ds_read_b64_tr_b16 v[176:177], v169 offset:4096
	ds_read_b64_tr_b16 v[178:179], v173 offset:4096
	v_add_f32_e32 v175, v175, v108
	v_add_f32_e32 v175, v175, v109
	v_add_f32_e32 v175, v175, v110
	v_add_f32_e32 v175, v175, v111
	s_waitcnt lgkmcnt(4)
	v_mfma_f32_32x32x16_bf16 v[64:79], v[204:207], v[10:13], v[64:79]
	ds_read_b64_tr_b16 v[184:185], v170 offset:4096
	ds_read_b64_tr_b16 v[186:187], v174 offset:4096
	v_max3_f32 v14, v80, v81, v82
	v_max3_f32 v14, v14, v83, v84
	v_max3_f32 v14, v14, v85, v86
	v_max3_f32 v14, v14, v87, v88
	s_waitcnt lgkmcnt(4)
	v_mfma_f32_32x32x16_bf16 v[48:63], v[208:211], v[10:13], v[48:63]
	v_max3_f32 v14, v14, v89, v90
	v_max3_f32 v14, v14, v91, v92
	v_max3_f32 v14, v14, v93, v94
	v_max_f32_e32 v14, v14, v95
	s_waitcnt lgkmcnt(2)
	v_mfma_f32_32x32x16_bf16 v[32:47], v[176:179], v[10:13], v[32:47]
	v_mov_b32_e32 v15, v14
	s_nop 1
	v_permlane32_swap_b32_e32 v14, v15
	s_waitcnt lgkmcnt(0)
	v_mfma_f32_32x32x16_bf16 v[16:31], v[184:187], v[10:13], v[16:31]
	v_max_f32_e32 v14, v14, v15
	v_cmp_lt_f32_e32 vcc, 2.0, v14
	s_cbranch_vccnz .Lat3_rare_a1
.Lat3_common_a1:
	s_cmp_eq_u32 s13, s12
	s_cbranch_scc1 .Lat3_tail_a
	s_waitcnt vmcnt(0)
	s_barrier
	s_add_i32 s11, s13, 2
	s_cmp_gt_u32 s11, s12
	s_cbranch_scc1 .Lat3_nodma_a
	s_add_u32 m0, s16, 40960
	v_lshl_add_u64 v[202:203], v[162:163], 0, s[54:55]
	global_load_lds_dwordx4 v[162:163], off
	v_lshl_add_u64 v[162:163], v[162:163], 0, s[60:61]
	s_add_u32 m0, s16, 49152
	s_nop 0
	global_load_lds_dwordx4 v[202:203], off
	s_cmp_eq_u64 s[6:7], 0
	s_cbranch_scc1 .Lat3_norope_a
	s_add_u32 m0, s16, 57344
	s_nop 0
	global_load_lds_dwordx4 v[160:161], off
	v_lshl_add_u64 v[160:161], v[160:161], 0, s[60:61]
.Lat3_norope_a:
.Lat3_nodma_a:
	ds_read_b128 v[220:223], v190 offset:20480
	ds_read_b128 v[224:227], v191 offset:20480
	ds_read_b128 v[228:231], v192 offset:20480
	v_exp_f32_e32 v80, v80
	v_exp_f32_e32 v81, v81
	v_exp_f32_e32 v82, v82
	v_exp_f32_e32 v83, v83
	s_waitcnt lgkmcnt(2)
	v_mfma_f32_32x32x16_bf16 v[96:111], v[220:223], v[148:151], v[232:247]
	ds_read_b128 v[220:223], v193 offset:20480
	v_exp_f32_e32 v84, v84
	v_exp_f32_e32 v85, v85
	s_waitcnt lgkmcnt(2)
	v_mfma_f32_32x32x16_bf16 v[96:111], v[224:227], v[144:147], v[96:111]
	ds_read_b128 v[224:227], v194 offset:20480
	v_cvt_pk_bf16_f32 v6, v80, v81
	v_exp_f32_e32 v86, v86
	s_waitcnt lgkmcnt(2)
	v_mfma_f32_32x32x16_bf16 v[96:111], v[228:231], v[140:143], v[96:111]
	ds_read_b128 v[228:231], v195 offset:20480
	v_exp_f32_e32 v87, v87
	v_cvt_pk_bf16_f32 v7, v82, v83
	s_waitcnt lgkmcnt(2)
	v_mfma_f32_32x32x16_bf16 v[96:111], v[220:223], v[136:139], v[96:111]
	ds_read_b128 v[220:223], v196 offset:20480
	v_cvt_pk_bf16_f32 v8, v84, v85
	v_exp_f32_e32 v88, v88
	s_waitcnt lgkmcnt(2)
	v_mfma_f32_32x32x16_bf16 v[96:111], v[224:227], v[132:135], v[96:111]
	ds_read_b128 v[224:227], v198 offset:20480
	v_exp_f32_e32 v89, v89
	v_cvt_pk_bf16_f32 v9, v86, v87
	s_waitcnt lgkmcnt(2)
	v_mfma_f32_32x32x16_bf16 v[96:111], v[228:231], v[128:131], v[96:111]
	ds_read_b128 v[228:231], v199 offset:36864
	v_exp_f32_e32 v90, v90
	v_exp_f32_e32 v91, v91
	s_waitcnt lgkmcnt(2)
	v_mfma_f32_32x32x16_bf16 v[96:111], v[220:223], v[124:127], v[96:111]
	ds_read_b128 v[220:223], v200 offset:36864
	v_cvt_pk_bf16_f32 v10, v88, v89
	v_exp_f32_e32 v92, v92
	s_waitcnt lgkmcnt(2)
	v_mfma_f32_32x32x16_bf16 v[96:111], v[224:227], v[120:123], v[96:111]
	ds_read_b64_tr_b16 v[204:205], v155 offset:8192
	ds_read_b64_tr_b16 v[206:207], v171 offset:8192
	v_exp_f32_e32 v93, v93
	v_cvt_pk_bf16_f32 v11, v90, v91
	s_waitcnt lgkmcnt(3)
	v_mfma_f32_32x32x16_bf16 v[96:111], v[228:231], v[116:119], v[96:111]
	ds_read_b64_tr_b16 v[208:209], v168 offset:8192
	ds_read_b64_tr_b16 v[210:211], v172 offset:8192
	v_exp_f32_e32 v94, v94
	v_exp_f32_e32 v95, v95
	s_waitcnt lgkmcnt(4)
	v_mfma_f32_32x32x16_bf16 v[96:111], v[220:223], v[112:115], v[96:111]
	ds_read_b64_tr_b16 v[176:177], v169 offset:8192
	ds_read_b64_tr_b16 v[178:179], v173 offset:8192
	v_cvt_pk_bf16_f32 v12, v92, v93
	v_cvt_pk_bf16_f32 v13, v94, v95
	s_waitcnt lgkmcnt(4)
	v_mfma_f32_32x32x16_bf16 v[64:79], v[204:207], v[6:9], v[64:79]
	ds_read_b64_tr_b16 v[184:185], v170 offset:8192
	ds_read_b64_tr_b16 v[186:187], v174 offset:8192
	v_add_f32_e32 v175, v175, v80
	v_add_f32_e32 v175, v175, v81
	v_add_f32_e32 v175, v175, v82
	v_add_f32_e32 v175, v175, v83
	s_waitcnt lgkmcnt(4)
	v_mfma_f32_32x32x16_bf16 v[48:63], v[208:211], v[6:9], v[48:63]
	ds_read_b64_tr_b16 v[204:205], v155 offset:12288
	ds_read_b64_tr_b16 v[206:207], v171 offset:12288
	v_add_f32_e32 v175, v175, v84
	v_add_f32_e32 v175, v175, v85
	v_add_f32_e32 v175, v175, v86
	v_add_f32_e32 v175, v175, v87
	s_waitcnt lgkmcnt(4)
	v_mfma_f32_32x32x16_bf16 v[32:47], v[176:179], v[6:9], v[32:47]
	ds_read_b64_tr_b16 v[208:209], v168 offset:12288
	ds_read_b64_tr_b16 v[210:211], v172 offset:12288
	v_add_f32_e32 v175, v175, v88
	v_add_f32_e32 v175, v175, v89
	v_add_f32_e32 v175, v175, v90
	v_add_f32_e32 v175, v175, v91
	s_waitcnt lgkmcnt(4)
	v_mfma_f32_32x32x16_bf16 v[16:31], v[184:187], v[6:9], v[16:31]
	ds_read_b64_tr_b16 v[176:177], v169 offset:12288
	ds_read_b64_tr_b16 v[178:179], v173 offset:12288
	v_add_f32_e32 v175, v175, v92
	v_add_f32_e32 v175, v175, v93
	v_add_f32_e32 v175, v175, v94
	v_add_f32_e32 v175, v175, v95
	s_add_i32 s11, s13, 1
	s_cmp_lg_u32 s11, s17
	s_cbranch_scc1 .Lat3_nomask_a2
	v_mov_b32_e32 v104, v164
	v_mov_b32_e32 v105, v164
	v_mov_b32_e32 v106, v164
	v_mov_b32_e32 v107, v164
	v_mov_b32_e32 v108, v164
	v_mov_b32_e32 v109, v164
	v_mov_b32_e32 v110, v164
	v_mov_b32_e32 v111, v164
.Lat3_nomask_a2:
	s_waitcnt lgkmcnt(4)
	v_mfma_f32_32x32x16_bf16 v[64:79], v[204:207], v[10:13], v[64:79]
	ds_read_b64_tr_b16 v[184:185], v170 offset:12288
	ds_read_b64_tr_b16 v[186:187], v174 offset:12288
	v_max3_f32 v14, v96, v97, v98
	v_max3_f32 v14, v14, v99, v100
	v_max3_f32 v14, v14, v101, v102
	v_max3_f32 v14, v14, v103, v104
	s_waitcnt lgkmcnt(4)
	v_mfma_f32_32x32x16_bf16 v[48:63], v[208:211], v[10:13], v[48:63]
	v_max3_f32 v14, v14, v105, v106
	v_max3_f32 v14, v14, v107, v108
	v_max3_f32 v14, v14, v109, v110
	v_max_f32_e32 v14, v14, v111
	s_waitcnt lgkmcnt(2)
	v_mfma_f32_32x32x16_bf16 v[32:47], v[176:179], v[10:13], v[32:47]
	v_mov_b32_e32 v15, v14
	s_nop 1
	v_permlane32_swap_b32_e32 v14, v15
	s_waitcnt lgkmcnt(0)
	v_mfma_f32_32x32x16_bf16 v[16:31], v[184:187], v[10:13], v[16:31]
	v_max_f32_e32 v14, v14, v15
	v_cmp_lt_f32_e32 vcc, 2.0, v14
	s_cbranch_vccnz .Lat3_rare_a2
.Lat3_common_a2:
	s_add_i32 s13, s13, 1
.Lat3_b:
	s_cmp_eq_u32 s13, s17
	s_cbranch_scc1 .Lat3_smp_b
	ds_read_b128 v[220:223], v190 offset:28672
	ds_read_b128 v[224:227], v191 offset:28672
	ds_read_b128 v[228:231], v192 offset:28672
	v_exp_f32_e32 v96, v96
	v_exp_f32_e32 v97, v97
	v_exp_f32_e32 v98, v98
	v_exp_f32_e32 v99, v99
	s_waitcnt lgkmcnt(2)
	v_mfma_f32_32x32x16_bf16 v[80:95], v[220:223], v[148:151], v[232:247]
	ds_read_b128 v[220:223], v193 offset:28672
	v_exp_f32_e32 v100, v100
	v_exp_f32_e32 v101, v101
	s_waitcnt lgkmcnt(2)
	v_mfma_f32_32x32x16_bf16 v[80:95], v[224:227], v[144:147], v[80:95]
	ds_read_b128 v[224:227], v194 offset:28672
	v_cvt_pk_bf16_f32 v6, v96, v97
	v_exp_f32_e32 v102, v102
	s_waitcnt lgkmcnt(2)
	v_mfma_f32_32x32x16_bf16 v[80:95], v[228:231], v[140:143], v[80:95]
	ds_read_b128 v[228:231], v195 offset:28672
	v_exp_f32_e32 v103, v103
	v_cvt_pk_bf16_f32 v7, v98, v99
	s_waitcnt lgkmcnt(2)
	v_mfma_f32_32x32x16_bf16 v[80:95], v[220:223], v[136:139], v[80:95]
	ds_read_b128 v[220:223], v196 offset:28672
	v_cvt_pk_bf16_f32 v8, v100, v101
	v_exp_f32_e32 v104, v104
	s_waitcnt lgkmcnt(2)
	v_mfma_f32_32x32x16_bf16 v[80:95], v[224:227], v[132:135], v[80:95]
	ds_read_b128 v[224:227], v198 offset:28672
	v_exp_f32_e32 v105, v105
	v_cvt_pk_bf16_f32 v9, v102, v103
	s_waitcnt lgkmcnt(2)
	v_mfma_f32_32x32x16_bf16 v[80:95], v[228:231], v[128:131], v[80:95]
	ds_read_b128 v[228:231], v199 offset:38912
	v_exp_f32_e32 v106, v106
	v_exp_f32_e32 v107, v107
	s_waitcnt lgkmcnt(2)
	v_mfma_f32_32x32x16_bf16 v[80:95], v[220:223], v[124:127], v[80:95]
	ds_read_b128 v[220:223], v200 offset:38912
	v_cvt_pk_bf16_f32 v10, v104, v105
	v_exp_f32_e32 v108, v108
	s_waitcnt lgkmcnt(2)
	v_mfma_f32_32x32x16_bf16 v[80:95], v[224:227], v[120:123], v[80:95]
	ds_read_b64_tr_b16 v[204:205], v155 offset:20480
	ds_read_b64_tr_b16 v[206:207], v171 offset:20480
	v_exp_f32_e32 v109, v109
	v_cvt_pk_bf16_f32 v11, v106, v107
	s_waitcnt lgkmcnt(3)
	v_mfma_f32_32x32x16_bf16 v[80:95], v[228:231], v[116:119], v[80:95]
	ds_read_b64_tr_b16 v[208:209], v168 offset:20480
	ds_read_b64_tr_b16 v[210:211], v172 offset:20480
	v_exp_f32_e32 v110, v110
	v_exp_f32_e32 v111, v111
	s_waitcnt lgkmcnt(4)
	v_mfma_f32_32x32x16_bf16 v[80:95], v[220:223], v[112:115], v[80:95]
	ds_read_b64_tr_b16 v[176:177], v169 offset:20480
	ds_read_b64_tr_b16 v[178:179], v173 offset:20480
	v_cvt_pk_bf16_f32 v12, v108, v109
	v_cvt_pk_bf16_f32 v13, v110, v111
	s_waitcnt lgkmcnt(4)
	v_mfma_f32_32x32x16_bf16 v[64:79], v[204:207], v[6:9], v[64:79]
	ds_read_b64_tr_b16 v[184:185], v170 offset:20480
	ds_read_b64_tr_b16 v[186:187], v174 offset:20480
	v_add_f32_e32 v175, v175, v96
	v_add_f32_e32 v175, v175, v97
	v_add_f32_e32 v175, v175, v98
	v_add_f32_e32 v175, v175, v99
	s_waitcnt lgkmcnt(4)
	v_mfma_f32_32x32x16_bf16 v[48:63], v[208:211], v[6:9], v[48:63]
	ds_read_b64_tr_b16 v[204:205], v155 offset:24576
	ds_read_b64_tr_b16 v[206:207], v171 offset:24576
	v_add_f32_e32 v175, v175, v100
	v_add_f32_e32 v175, v175, v101
	v_add_f32_e32 v175, v175, v102
	v_add_f32_e32 v175, v175, v103
	s_waitcnt lgkmcnt(4)
	v_mfma_f32_32x32x16_bf16 v[32:47], v[176:179], v[6:9], v[32:47]
	ds_read_b64_tr_b16 v[208:209], v168 offset:24576
	ds_read_b64_tr_b16 v[210:211], v172 offset:24576
	v_add_f32_e32 v175, v175, v104
	v_add_f32_e32 v175, v175, v105
	v_add_f32_e32 v175, v175, v106
	v_add_f32_e32 v175, v175, v107
	s_waitcnt lgkmcnt(4)
	v_mfma_f32_32x32x16_bf16 v[16:31], v[184:187], v[6:9], v[16:31]
	ds_read_b64_tr_b16 v[176:177], v169 offset:24576
	ds_read_b64_tr_b16 v[178:179], v173 offset:24576
	v_add_f32_e32 v175, v175, v108
	v_add_f32_e32 v175, v175, v109
	v_add_f32_e32 v175, v175, v110
	v_add_f32_e32 v175, v175, v111
	s_waitcnt lgkmcnt(4)
	v_mfma_f32_32x32x16_bf16 v[64:79], v[204:207], v[10:13], v[64:79]
	ds_read_b64_tr_b16 v[184:185], v170 offset:24576
	ds_read_b64_tr_b16 v[186:187], v174 offset:24576
	v_max3_f32 v14, v80, v81, v82
	v_max3_f32 v14, v14, v83, v84
	v_max3_f32 v14, v14, v85, v86
	v_max3_f32 v14, v14, v87, v88
	s_waitcnt lgkmcnt(4)
	v_mfma_f32_32x32x16_bf16 v[48:63], v[208:211], v[10:13], v[48:63]
	v_max3_f32 v14, v14, v89, v90
	v_max3_f32 v14, v14, v91, v92
	v_max3_f32 v14, v14, v93, v94
	v_max_f32_e32 v14, v14, v95
	s_waitcnt lgkmcnt(2)
	v_mfma_f32_32x32x16_bf16 v[32:47], v[176:179], v[10:13], v[32:47]
	v_mov_b32_e32 v15, v14
	s_nop 1
	v_permlane32_swap_b32_e32 v14, v15
	s_waitcnt lgkmcnt(0)
	v_mfma_f32_32x32x16_bf16 v[16:31], v[184:187], v[10:13], v[16:31]
	v_max_f32_e32 v14, v14, v15
	v_cmp_lt_f32_e32 vcc, 2.0, v14
	s_cbranch_vccnz .Lat3_rare_b1
.Lat3_common_b1:
	s_cmp_eq_u32 s13, s12
	s_cbranch_scc1 .Lat3_tail_b
	s_waitcnt vmcnt(0)
	s_barrier
	s_add_i32 s11, s13, 2
	s_cmp_gt_u32 s11, s12
	s_cbranch_scc1 .Lat3_nodma_b
	s_add_u32 m0, s16, 0
	v_lshl_add_u64 v[202:203], v[162:163], 0, s[54:55]
	global_load_lds_dwordx4 v[162:163], off
	v_lshl_add_u64 v[162:163], v[162:163], 0, s[60:61]
	s_add_u32 m0, s16, 8192
	s_nop 0
	global_load_lds_dwordx4 v[202:203], off
	s_cmp_eq_u64 s[6:7], 0
	s_cbranch_scc1 .Lat3_norope_b
	s_add_u32 m0, s16, 16384
	s_nop 0
	global_load_lds_dwordx4 v[160:161], off
	v_lshl_add_u64 v[160:161], v[160:161], 0, s[60:61]
.Lat3_norope_b:
.Lat3_nodma_b:
	ds_read_b128 v[220:223], v190 offset:40960
	ds_read_b128 v[224:227], v191 offset:40960
	ds_read_b128 v[228:231], v192 offset:40960
	v_exp_f32_e32 v80, v80
	v_exp_f32_e32 v81, v81
	v_exp_f32_e32 v82, v82
	v_exp_f32_e32 v83, v83
	s_waitcnt lgkmcnt(2)
	v_mfma_f32_32x32x16_bf16 v[96:111], v[220:223], v[148:151], v[232:247]
	ds_read_b128 v[220:223], v193 offset:40960
	v_exp_f32_e32 v84, v84
	v_exp_f32_e32 v85, v85
	s_waitcnt lgkmcnt(2)
	v_mfma_f32_32x32x16_bf16 v[96:111], v[224:227], v[144:147], v[96:111]
	ds_read_b128 v[224:227], v194 offset:40960
	v_cvt_pk_bf16_f32 v6, v80, v81
	v_exp_f32_e32 v86, v86
	s_waitcnt lgkmcnt(2)
	v_mfma_f32_32x32x16_bf16 v[96:111], v[228:231], v[140:143], v[96:111]
	ds_read_b128 v[228:231], v195 offset:40960
	v_exp_f32_e32 v87, v87
	v_cvt_pk_bf16_f32 v7, v82, v83
	s_waitcnt lgkmcnt(2)
	v_mfma_f32_32x32x16_bf16 v[96:111], v[220:223], v[136:139], v[96:111]
	ds_read_b128 v[220:223], v196 offset:40960
	v_cvt_pk_bf16_f32 v8, v84, v85
	v_exp_f32_e32 v88, v88
	s_waitcnt lgkmcnt(2)
	v_mfma_f32_32x32x16_bf16 v[96:111], v[224:227], v[132:135], v[96:111]
	ds_read_b128 v[224:227], v198 offset:40960
	v_exp_f32_e32 v89, v89
	v_cvt_pk_bf16_f32 v9, v86, v87
	s_waitcnt lgkmcnt(2)
	v_mfma_f32_32x32x16_bf16 v[96:111], v[228:231], v[128:131], v[96:111]
	ds_read_b128 v[228:231], v199 offset:57344
	v_exp_f32_e32 v90, v90
	v_exp_f32_e32 v91, v91
	s_waitcnt lgkmcnt(2)
	v_mfma_f32_32x32x16_bf16 v[96:111], v[220:223], v[124:127], v[96:111]
	ds_read_b128 v[220:223], v200 offset:57344
	v_cvt_pk_bf16_f32 v10, v88, v89
	v_exp_f32_e32 v92, v92
	s_waitcnt lgkmcnt(2)
	v_mfma_f32_32x32x16_bf16 v[96:111], v[224:227], v[120:123], v[96:111]
	ds_read_b64_tr_b16 v[204:205], v155 offset:28672
	ds_read_b64_tr_b16 v[206:207], v171 offset:28672
	v_exp_f32_e32 v93, v93
	v_cvt_pk_bf16_f32 v11, v90, v91
	s_waitcnt lgkmcnt(3)
	v_mfma_f32_32x32x16_bf16 v[96:111], v[228:231], v[116:119], v[96:111]
	ds_read_b64_tr_b16 v[208:209], v168 offset:28672
	ds_read_b64_tr_b16 v[210:211], v172 offset:28672
	v_exp_f32_e32 v94, v94
	v_exp_f32_e32 v95, v95
	s_waitcnt lgkmcnt(4)
	v_mfma_f32_32x32x16_bf16 v[96:111], v[220:223], v[112:115], v[96:111]
	ds_read_b64_tr_b16 v[176:177], v169 offset:28672
	ds_read_b64_tr_b16 v[178:179], v173 offset:28672
	v_cvt_pk_bf16_f32 v12, v92, v93
	v_cvt_pk_bf16_f32 v13, v94, v95
	s_waitcnt lgkmcnt(4)
	v_mfma_f32_32x32x16_bf16 v[64:79], v[204:207], v[6:9], v[64:79]
	ds_read_b64_tr_b16 v[184:185], v170 offset:28672
	ds_read_b64_tr_b16 v[186:187], v174 offset:28672
	v_add_f32_e32 v175, v175, v80
	v_add_f32_e32 v175, v175, v81
	v_add_f32_e32 v175, v175, v82
	v_add_f32_e32 v175, v175, v83
	s_waitcnt lgkmcnt(4)
	v_mfma_f32_32x32x16_bf16 v[48:63], v[208:211], v[6:9], v[48:63]
	ds_read_b64_tr_b16 v[204:205], v155 offset:32768
	ds_read_b64_tr_b16 v[206:207], v171 offset:32768
	v_add_f32_e32 v175, v175, v84
	v_add_f32_e32 v175, v175, v85
	v_add_f32_e32 v175, v175, v86
	v_add_f32_e32 v175, v175, v87
	s_waitcnt lgkmcnt(4)
	v_mfma_f32_32x32x16_bf16 v[32:47], v[176:179], v[6:9], v[32:47]
	ds_read_b64_tr_b16 v[208:209], v168 offset:32768
	ds_read_b64_tr_b16 v[210:211], v172 offset:32768
	v_add_f32_e32 v175, v175, v88
	v_add_f32_e32 v175, v175, v89
	v_add_f32_e32 v175, v175, v90
	v_add_f32_e32 v175, v175, v91
	s_waitcnt lgkmcnt(4)
	v_mfma_f32_32x32x16_bf16 v[16:31], v[184:187], v[6:9], v[16:31]
	ds_read_b64_tr_b16 v[176:177], v169 offset:32768
	ds_read_b64_tr_b16 v[178:179], v173 offset:32768
	v_add_f32_e32 v175, v175, v92
	v_add_f32_e32 v175, v175, v93
	v_add_f32_e32 v175, v175, v94
	v_add_f32_e32 v175, v175, v95
	s_add_i32 s11, s13, 1
	s_cmp_lg_u32 s11, s17
	s_cbranch_scc1 .Lat3_nomask_b2
	v_mov_b32_e32 v104, v164
	v_mov_b32_e32 v105, v164
	v_mov_b32_e32 v106, v164
	v_mov_b32_e32 v107, v164
	v_mov_b32_e32 v108, v164
	v_mov_b32_e32 v109, v164
	v_mov_b32_e32 v110, v164
	v_mov_b32_e32 v111, v164
.Lat3_nomask_b2:
	s_waitcnt lgkmcnt(4)
	v_mfma_f32_32x32x16_bf16 v[64:79], v[204:207], v[10:13], v[64:79]
	ds_read_b64_tr_b16 v[184:185], v170 offset:32768
	ds_read_b64_tr_b16 v[186:187], v174 offset:32768
	v_max3_f32 v14, v96, v97, v98
	v_max3_f32 v14, v14, v99, v100
	v_max3_f32 v14, v14, v101, v102
	v_max3_f32 v14, v14, v103, v104
	s_waitcnt lgkmcnt(4)
	v_mfma_f32_32x32x16_bf16 v[48:63], v[208:211], v[10:13], v[48:63]
	v_max3_f32 v14, v14, v105, v106
	v_max3_f32 v14, v14, v107, v108
	v_max3_f32 v14, v14, v109, v110
	v_max_f32_e32 v14, v14, v111
	s_waitcnt lgkmcnt(2)
	v_mfma_f32_32x32x16_bf16 v[32:47], v[176:179], v[10:13], v[32:47]
	v_mov_b32_e32 v15, v14
	s_nop 1
	v_permlane32_swap_b32_e32 v14, v15
	s_waitcnt lgkmcnt(0)
	v_mfma_f32_32x32x16_bf16 v[16:31], v[184:187], v[10:13], v[16:31]
	v_max_f32_e32 v14, v14, v15
	v_cmp_lt_f32_e32 vcc, 2.0, v14
	s_cbranch_vccnz .Lat3_rare_b2

.Lat3_c:
	s_cmp_eq_u32 s13, s17
	s_cbranch_scc1 .Lat3_smp_c
	ds_read_b128 v[220:223], v190 offset:49152
	ds_read_b128 v[224:227], v191 offset:49152
	ds_read_b128 v[228:231], v192 offset:49152
	v_exp_f32_e32 v96, v96
	v_exp_f32_e32 v97, v97
	v_exp_f32_e32 v98, v98
	v_exp_f32_e32 v99, v99
	s_waitcnt lgkmcnt(2)
	v_mfma_f32_32x32x16_bf16 v[80:95], v[220:223], v[148:151], v[232:247]
	ds_read_b128 v[220:223], v193 offset:49152
	v_exp_f32_e32 v100, v100
	v_exp_f32_e32 v101, v101
	s_waitcnt lgkmcnt(2)
	v_mfma_f32_32x32x16_bf16 v[80:95], v[224:227], v[144:147], v[80:95]
	ds_read_b128 v[224:227], v194 offset:49152
	v_cvt_pk_bf16_f32 v6, v96, v97
	v_exp_f32_e32 v102, v102
	s_waitcnt lgkmcnt(2)
	v_mfma_f32_32x32x16_bf16 v[80:95], v[228:231], v[140:143], v[80:95]
	ds_read_b128 v[228:231], v195 offset:49152
	v_exp_f32_e32 v103, v103
	v_cvt_pk_bf16_f32 v7, v98, v99
	s_waitcnt lgkmcnt(2)
	v_mfma_f32_32x32x16_bf16 v[80:95], v[220:223], v[136:139], v[80:95]
	ds_read_b128 v[220:223], v196 offset:49152
	v_cvt_pk_bf16_f32 v8, v100, v101
	v_exp_f32_e32 v104, v104
	s_waitcnt lgkmcnt(2)
	v_mfma_f32_32x32x16_bf16 v[80:95], v[224:227], v[132:135], v[80:95]
	ds_read_b128 v[224:227], v198 offset:49152
	v_exp_f32_e32 v105, v105
	v_cvt_pk_bf16_f32 v9, v102, v103
	s_waitcnt lgkmcnt(2)
	v_mfma_f32_32x32x16_bf16 v[80:95], v[228:231], v[128:131], v[80:95]
	ds_read_b128 v[228:231], v199 offset:59392
	v_exp_f32_e32 v106, v106
	v_exp_f32_e32 v107, v107
	s_waitcnt lgkmcnt(2)
	v_mfma_f32_32x32x16_bf16 v[80:95], v[220:223], v[124:127], v[80:95]
	ds_read_b128 v[220:223], v200 offset:59392
	v_cvt_pk_bf16_f32 v10, v104, v105
	v_exp_f32_e32 v108, v108
	s_waitcnt lgkmcnt(2)
	v_mfma_f32_32x32x16_bf16 v[80:95], v[224:227], v[120:123], v[80:95]
	ds_read_b64_tr_b16 v[204:205], v155 offset:40960
	ds_read_b64_tr_b16 v[206:207], v171 offset:40960
	v_exp_f32_e32 v109, v109
	v_cvt_pk_bf16_f32 v11, v106, v107
	s_waitcnt lgkmcnt(3)
	v_mfma_f32_32x32x16_bf16 v[80:95], v[228:231], v[116:119], v[80:95]
	ds_read_b64_tr_b16 v[208:209], v168 offset:40960
	ds_read_b64_tr_b16 v[210:211], v172 offset:40960
	v_exp_f32_e32 v110, v110
	v_exp_f32_e32 v111, v111
	s_waitcnt lgkmcnt(4)
	v_mfma_f32_32x32x16_bf16 v[80:95], v[220:223], v[112:115], v[80:95]
	ds_read_b64_tr_b16 v[176:177], v169 offset:40960
	ds_read_b64_tr_b16 v[178:179], v173 offset:40960
	v_cvt_pk_bf16_f32 v12, v108, v109
	v_cvt_pk_bf16_f32 v13, v110, v111
	s_waitcnt lgkmcnt(4)
	v_mfma_f32_32x32x16_bf16 v[64:79], v[204:207], v[6:9], v[64:79]
	ds_read_b64_tr_b16 v[184:185], v170 offset:40960
	ds_read_b64_tr_b16 v[186:187], v174 offset:40960
	v_add_f32_e32 v175, v175, v96
	v_add_f32_e32 v175, v175, v97
	v_add_f32_e32 v175, v175, v98
	v_add_f32_e32 v175, v175, v99
	s_waitcnt lgkmcnt(4)
	v_mfma_f32_32x32x16_bf16 v[48:63], v[208:211], v[6:9], v[48:63]
	ds_read_b64_tr_b16 v[204:205], v155 offset:45056
	ds_read_b64_tr_b16 v[206:207], v171 offset:45056
	v_add_f32_e32 v175, v175, v100
	v_add_f32_e32 v175, v175, v101
	v_add_f32_e32 v175, v175, v102
	v_add_f32_e32 v175, v175, v103
	s_waitcnt lgkmcnt(4)
	v_mfma_f32_32x32x16_bf16 v[32:47], v[176:179], v[6:9], v[32:47]
	ds_read_b64_tr_b16 v[208:209], v168 offset:45056
	ds_read_b64_tr_b16 v[210:211], v172 offset:45056
	v_add_f32_e32 v175, v175, v104
	v_add_f32_e32 v175, v175, v105
	v_add_f32_e32 v175, v175, v106
	v_add_f32_e32 v175, v175, v107
	s_waitcnt lgkmcnt(4)
	v_mfma_f32_32x32x16_bf16 v[16:31], v[184:187], v[6:9], v[16:31]
	ds_read_b64_tr_b16 v[176:177], v169 offset:45056
	ds_read_b64_tr_b16 v[178:179], v173 offset:45056
	v_add_f32_e32 v175, v175, v108
	v_add_f32_e32 v175, v175, v109
	v_add_f32_e32 v175, v175, v110
	v_add_f32_e32 v175, v175, v111
	s_waitcnt lgkmcnt(4)
	v_mfma_f32_32x32x16_bf16 v[64:79], v[204:207], v[10:13], v[64:79]
	ds_read_b64_tr_b16 v[184:185], v170 offset:45056
	ds_read_b64_tr_b16 v[186:187], v174 offset:45056
	v_max3_f32 v14, v80, v81, v82
	v_max3_f32 v14, v14, v83, v84
	v_max3_f32 v14, v14, v85, v86
	v_max3_f32 v14, v14, v87, v88
	s_waitcnt lgkmcnt(4)
	v_mfma_f32_32x32x16_bf16 v[48:63], v[208:211], v[10:13], v[48:63]
	v_max3_f32 v14, v14, v89, v90
	v_max3_f32 v14, v14, v91, v92
	v_max3_f32 v14, v14, v93, v94
	v_max_f32_e32 v14, v14, v95
	s_waitcnt lgkmcnt(2)
	v_mfma_f32_32x32x16_bf16 v[32:47], v[176:179], v[10:13], v[32:47]
	v_mov_b32_e32 v15, v14
	s_nop 1
	v_permlane32_swap_b32_e32 v14, v15
	s_waitcnt lgkmcnt(0)
	v_mfma_f32_32x32x16_bf16 v[16:31], v[184:187], v[10:13], v[16:31]
	v_max_f32_e32 v14, v14, v15
	v_cmp_lt_f32_e32 vcc, 2.0, v14
	s_cbranch_vccnz .Lat3_rare_c1
.Lat3_common_c1:
	s_cmp_eq_u32 s13, s12
	s_cbranch_scc1 .Lat3_tail_c
	s_waitcnt vmcnt(0)
	s_barrier
	s_add_i32 s11, s13, 2
	s_cmp_gt_u32 s11, s12
	s_cbranch_scc1 .Lat3_nodma_c
	s_add_u32 m0, s16, 20480
	v_lshl_add_u64 v[202:203], v[162:163], 0, s[54:55]
	global_load_lds_dwordx4 v[162:163], off
	v_lshl_add_u64 v[162:163], v[162:163], 0, s[60:61]
	s_add_u32 m0, s16, 28672
	s_nop 0
	global_load_lds_dwordx4 v[202:203], off
	s_cmp_eq_u64 s[6:7], 0
	s_cbranch_scc1 .Lat3_norope_c
	s_add_u32 m0, s16, 36864
	s_nop 0
	global_load_lds_dwordx4 v[160:161], off
	v_lshl_add_u64 v[160:161], v[160:161], 0, s[60:61]
.Lat3_norope_c:
.Lat3_nodma_c:
	ds_read_b128 v[220:223], v190 offset:0
	ds_read_b128 v[224:227], v191 offset:0
	ds_read_b128 v[228:231], v192 offset:0
	v_exp_f32_e32 v80, v80
	v_exp_f32_e32 v81, v81
	v_exp_f32_e32 v82, v82
	v_exp_f32_e32 v83, v83
	s_waitcnt lgkmcnt(2)
	v_mfma_f32_32x32x16_bf16 v[96:111], v[220:223], v[148:151], v[232:247]
	ds_read_b128 v[220:223], v193 offset:0
	v_exp_f32_e32 v84, v84
	v_exp_f32_e32 v85, v85
	s_waitcnt lgkmcnt(2)
	v_mfma_f32_32x32x16_bf16 v[96:111], v[224:227], v[144:147], v[96:111]
	ds_read_b128 v[224:227], v194 offset:0
	v_cvt_pk_bf16_f32 v6, v80, v81
	v_exp_f32_e32 v86, v86
	s_waitcnt lgkmcnt(2)
	v_mfma_f32_32x32x16_bf16 v[96:111], v[228:231], v[140:143], v[96:111]
	ds_read_b128 v[228:231], v195 offset:0
	v_exp_f32_e32 v87, v87
	v_cvt_pk_bf16_f32 v7, v82, v83
	s_waitcnt lgkmcnt(2)
	v_mfma_f32_32x32x16_bf16 v[96:111], v[220:223], v[136:139], v[96:111]
	ds_read_b128 v[220:223], v196 offset:0
	v_cvt_pk_bf16_f32 v8, v84, v85
	v_exp_f32_e32 v88, v88
	s_waitcnt lgkmcnt(2)
	v_mfma_f32_32x32x16_bf16 v[96:111], v[224:227], v[132:135], v[96:111]
	ds_read_b128 v[224:227], v198 offset:0
	v_exp_f32_e32 v89, v89
	v_cvt_pk_bf16_f32 v9, v86, v87
	s_waitcnt lgkmcnt(2)
	v_mfma_f32_32x32x16_bf16 v[96:111], v[228:231], v[128:131], v[96:111]
	ds_read_b128 v[228:231], v199 offset:16384
	v_exp_f32_e32 v90, v90
	v_exp_f32_e32 v91, v91
	s_waitcnt lgkmcnt(2)
	v_mfma_f32_32x32x16_bf16 v[96:111], v[220:223], v[124:127], v[96:111]
	ds_read_b128 v[220:223], v200 offset:16384
	v_cvt_pk_bf16_f32 v10, v88, v89
	v_exp_f32_e32 v92, v92
	s_waitcnt lgkmcnt(2)
	v_mfma_f32_32x32x16_bf16 v[96:111], v[224:227], v[120:123], v[96:111]
	ds_read_b64_tr_b16 v[204:205], v155 offset:49152
	ds_read_b64_tr_b16 v[206:207], v171 offset:49152
	v_exp_f32_e32 v93, v93
	v_cvt_pk_bf16_f32 v11, v90, v91
	s_waitcnt lgkmcnt(3)
	v_mfma_f32_32x32x16_bf16 v[96:111], v[228:231], v[116:119], v[96:111]
	ds_read_b64_tr_b16 v[208:209], v168 offset:49152
	ds_read_b64_tr_b16 v[210:211], v172 offset:49152
	v_exp_f32_e32 v94, v94
	v_exp_f32_e32 v95, v95
	s_waitcnt lgkmcnt(4)
	v_mfma_f32_32x32x16_bf16 v[96:111], v[220:223], v[112:115], v[96:111]
	ds_read_b64_tr_b16 v[176:177], v169 offset:49152
	ds_read_b64_tr_b16 v[178:179], v173 offset:49152
	v_cvt_pk_bf16_f32 v12, v92, v93
	v_cvt_pk_bf16_f32 v13, v94, v95
	s_waitcnt lgkmcnt(4)
	v_mfma_f32_32x32x16_bf16 v[64:79], v[204:207], v[6:9], v[64:79]
	ds_read_b64_tr_b16 v[184:185], v170 offset:49152
	ds_read_b64_tr_b16 v[186:187], v174 offset:49152
	v_add_f32_e32 v175, v175, v80
	v_add_f32_e32 v175, v175, v81
	v_add_f32_e32 v175, v175, v82
	v_add_f32_e32 v175, v175, v83
	s_waitcnt lgkmcnt(4)
	v_mfma_f32_32x32x16_bf16 v[48:63], v[208:211], v[6:9], v[48:63]
	ds_read_b64_tr_b16 v[204:205], v155 offset:53248
	ds_read_b64_tr_b16 v[206:207], v171 offset:53248
	v_add_f32_e32 v175, v175, v84
	v_add_f32_e32 v175, v175, v85
	v_add_f32_e32 v175, v175, v86
	v_add_f32_e32 v175, v175, v87
	s_waitcnt lgkmcnt(4)
	v_mfma_f32_32x32x16_bf16 v[32:47], v[176:179], v[6:9], v[32:47]
	ds_read_b64_tr_b16 v[208:209], v168 offset:53248
	ds_read_b64_tr_b16 v[210:211], v172 offset:53248
	v_add_f32_e32 v175, v175, v88
	v_add_f32_e32 v175, v175, v89
	v_add_f32_e32 v175, v175, v90
	v_add_f32_e32 v175, v175, v91
	s_waitcnt lgkmcnt(4)
	v_mfma_f32_32x32x16_bf16 v[16:31], v[184:187], v[6:9], v[16:31]
	ds_read_b64_tr_b16 v[176:177], v169 offset:53248
	ds_read_b64_tr_b16 v[178:179], v173 offset:53248
	v_add_f32_e32 v175, v175, v92
	v_add_f32_e32 v175, v175, v93
	v_add_f32_e32 v175, v175, v94
	v_add_f32_e32 v175, v175, v95
	s_add_i32 s11, s13, 1
	s_cmp_lg_u32 s11, s17
	s_cbranch_scc1 .Lat3_nomask_c2
	v_mov_b32_e32 v104, v164
	v_mov_b32_e32 v105, v164
	v_mov_b32_e32 v106, v164
	v_mov_b32_e32 v107, v164
	v_mov_b32_e32 v108, v164
	v_mov_b32_e32 v109, v164
	v_mov_b32_e32 v110, v164
	v_mov_b32_e32 v111, v164
.Lat3_nomask_c2:
	s_waitcnt lgkmcnt(4)
	v_mfma_f32_32x32x16_bf16 v[64:79], v[204:207], v[10:13], v[64:79]
	ds_read_b64_tr_b16 v[184:185], v170 offset:53248
	ds_read_b64_tr_b16 v[186:187], v174 offset:53248
	v_max3_f32 v14, v96, v97, v98
	v_max3_f32 v14, v14, v99, v100
	v_max3_f32 v14, v14, v101, v102
	v_max3_f32 v14, v14, v103, v104
	s_waitcnt lgkmcnt(4)
	v_mfma_f32_32x32x16_bf16 v[48:63], v[208:211], v[10:13], v[48:63]
	v_max3_f32 v14, v14, v105, v106
	v_max3_f32 v14, v14, v107, v108
	v_max3_f32 v14, v14, v109, v110
	v_max_f32_e32 v14, v14, v111
	s_waitcnt lgkmcnt(2)
	v_mfma_f32_32x32x16_bf16 v[32:47], v[176:179], v[10:13], v[32:47]
	v_mov_b32_e32 v15, v14
	s_nop 1
	v_permlane32_swap_b32_e32 v14, v15
	s_waitcnt lgkmcnt(0)
	v_mfma_f32_32x32x16_bf16 v[16:31], v[184:187], v[10:13], v[16:31]
	v_max_f32_e32 v14, v14, v15
	v_cmp_lt_f32_e32 vcc, 2.0, v14
	s_cbranch_vccnz .Lat3_rare_c2
.Lat3_common_c2:
	s_add_i32 s13, s13, 1
	s_branch .Lat3_a
.Lat3_tail_a:
	ds_read_b64_tr_b16 v[204:205], v155 offset:8192
	ds_read_b64_tr_b16 v[206:207], v171 offset:8192
	ds_read_b64_tr_b16 v[208:209], v168 offset:8192
	ds_read_b64_tr_b16 v[210:211], v172 offset:8192
	ds_read_b64_tr_b16 v[176:177], v169 offset:8192
	ds_read_b64_tr_b16 v[178:179], v173 offset:8192
	ds_read_b64_tr_b16 v[184:185], v170 offset:8192
	ds_read_b64_tr_b16 v[186:187], v174 offset:8192
	v_and_b32_e32 v3, 63, v165
	v_lshlrev_b32_e32 v3, 4, v3
	v_lshl_add_u32 v3, v154, 14, v3
	v_add_u32_e32 v4, 0x1000, v3
	v_add_u32_e32 v5, 0x2000, v3
	v_add_u32_e32 v213, 0x3000, v3
	global_load_dwordx4 v[148:151], v3, s[48:49] offset:0
	global_load_dwordx4 v[144:147], v5, s[48:49] offset:0
	global_load_dwordx4 v[140:143], v3, s[48:49] offset:1024
	global_load_dwordx4 v[136:139], v5, s[48:49] offset:1024
	global_load_dwordx4 v[132:135], v3, s[48:49] offset:2048
	global_load_dwordx4 v[128:131], v5, s[48:49] offset:2048
	global_load_dwordx4 v[124:127], v3, s[48:49] offset:3072
	global_load_dwordx4 v[120:123], v5, s[48:49] offset:3072
	global_load_dwordx4 v[116:119], v4, s[48:49] offset:0
	global_load_dwordx4 v[112:115], v213, s[48:49] offset:0
	global_load_dwordx4 v[220:223], v4, s[48:49] offset:1024
	global_load_dwordx4 v[224:227], v213, s[48:49] offset:1024
	global_load_dwordx4 v[228:231], v4, s[48:49] offset:2048
	global_load_dwordx4 v[96:99], v213, s[48:49] offset:2048
	global_load_dwordx4 v[100:103], v4, s[48:49] offset:3072
	global_load_dwordx4 v[104:107], v213, s[48:49] offset:3072
	v_and_b32_e32 v212, 0xffffffc0, v165
	v_lshlrev_b32_e32 v212, 1, v212
	v_lshl_add_u32 v212, v152, 10, v212
	v_lshl_add_u32 v212, v166, 1, v212
	global_load_dwordx2 v[190:191], v212, s[50:51] offset:0
	global_load_dwordx2 v[192:193], v212, s[50:51] offset:16
	global_load_dwordx2 v[194:195], v212, s[50:51] offset:32
	global_load_dwordx2 v[198:199], v212, s[50:51] offset:48
	global_load_dwordx2 v[200:201], v212, s[50:51] offset:64
	global_load_dwordx2 v[202:203], v212, s[50:51] offset:80
	global_load_dwordx2 v[216:217], v212, s[50:51] offset:96
	global_load_dwordx2 v[248:249], v212, s[50:51] offset:112
	v_exp_f32_e32 v80, v80
	v_exp_f32_e32 v81, v81
	v_exp_f32_e32 v82, v82
	v_exp_f32_e32 v83, v83
	v_exp_f32_e32 v84, v84
	v_exp_f32_e32 v85, v85
	v_cvt_pk_bf16_f32 v6, v80, v81
	v_exp_f32_e32 v86, v86
	v_exp_f32_e32 v87, v87
	v_cvt_pk_bf16_f32 v7, v82, v83
	v_cvt_pk_bf16_f32 v8, v84, v85
	v_exp_f32_e32 v88, v88
	v_exp_f32_e32 v89, v89
	v_cvt_pk_bf16_f32 v9, v86, v87
	s_nop 1
	s_waitcnt lgkmcnt(6)
	v_mfma_f32_32x32x16_bf16 v[64:79], v[204:207], v[6:9], v[64:79]
	ds_read_b64_tr_b16 v[204:205], v155 offset:12288
	ds_read_b64_tr_b16 v[206:207], v171 offset:12288
	v_exp_f32_e32 v90, v90
	v_exp_f32_e32 v91, v91
	v_cvt_pk_bf16_f32 v10, v88, v89
	s_waitcnt lgkmcnt(6)
	v_mfma_f32_32x32x16_bf16 v[48:63], v[208:211], v[6:9], v[48:63]
	ds_read_b64_tr_b16 v[208:209], v168 offset:12288
	ds_read_b64_tr_b16 v[210:211], v172 offset:12288
	v_exp_f32_e32 v92, v92
	v_exp_f32_e32 v93, v93
	v_cvt_pk_bf16_f32 v11, v90, v91
	s_waitcnt lgkmcnt(6)
	v_mfma_f32_32x32x16_bf16 v[32:47], v[176:179], v[6:9], v[32:47]
	ds_read_b64_tr_b16 v[176:177], v169 offset:12288
	ds_read_b64_tr_b16 v[178:179], v173 offset:12288
	v_exp_f32_e32 v94, v94
	v_exp_f32_e32 v95, v95
	s_waitcnt lgkmcnt(6)
	v_mfma_f32_32x32x16_bf16 v[16:31], v[184:187], v[6:9], v[16:31]
	ds_read_b64_tr_b16 v[184:185], v170 offset:12288
	ds_read_b64_tr_b16 v[186:187], v174 offset:12288
	v_cvt_pk_bf16_f32 v12, v92, v93
	v_cvt_pk_bf16_f32 v13, v94, v95
	s_nop 1
	s_waitcnt lgkmcnt(6)
	v_mfma_f32_32x32x16_bf16 v[64:79], v[204:207], v[10:13], v[64:79]
	v_add_f32_e32 v175, v175, v80
	v_add_f32_e32 v175, v175, v81
	v_add_f32_e32 v175, v175, v82
	v_add_f32_e32 v175, v175, v83
	s_waitcnt lgkmcnt(4)
	v_mfma_f32_32x32x16_bf16 v[48:63], v[208:211], v[10:13], v[48:63]
	v_add_f32_e32 v175, v175, v84
	v_add_f32_e32 v175, v175, v85
	v_add_f32_e32 v175, v175, v86
	v_add_f32_e32 v175, v175, v87
	s_waitcnt lgkmcnt(2)
	v_mfma_f32_32x32x16_bf16 v[32:47], v[176:179], v[10:13], v[32:47]
	v_add_f32_e32 v175, v175, v88
	v_add_f32_e32 v175, v175, v89
	v_add_f32_e32 v175, v175, v90
	v_add_f32_e32 v175, v175, v91
	s_waitcnt lgkmcnt(0)
	v_mfma_f32_32x32x16_bf16 v[16:31], v[184:187], v[10:13], v[16:31]
	v_add_f32_e32 v175, v175, v92
	v_add_f32_e32 v175, v175, v93
	v_add_f32_e32 v175, v175, v94
	v_add_f32_e32 v175, v175, v95
	s_branch .Lat3_epi_b
.Lat3_tail_b:
	ds_read_b64_tr_b16 v[204:205], v155 offset:28672
	ds_read_b64_tr_b16 v[206:207], v171 offset:28672
	ds_read_b64_tr_b16 v[208:209], v168 offset:28672
	ds_read_b64_tr_b16 v[210:211], v172 offset:28672
	ds_read_b64_tr_b16 v[176:177], v169 offset:28672
	ds_read_b64_tr_b16 v[178:179], v173 offset:28672
	ds_read_b64_tr_b16 v[184:185], v170 offset:28672
	ds_read_b64_tr_b16 v[186:187], v174 offset:28672
	v_and_b32_e32 v3, 63, v165
	v_lshlrev_b32_e32 v3, 4, v3
	v_lshl_add_u32 v3, v154, 14, v3
	v_add_u32_e32 v4, 0x1000, v3
	v_add_u32_e32 v5, 0x2000, v3
	v_add_u32_e32 v213, 0x3000, v3
	global_load_dwordx4 v[148:151], v3, s[48:49] offset:0
	global_load_dwordx4 v[144:147], v5, s[48:49] offset:0
	global_load_dwordx4 v[140:143], v3, s[48:49] offset:1024
	global_load_dwordx4 v[136:139], v5, s[48:49] offset:1024
	global_load_dwordx4 v[132:135], v3, s[48:49] offset:2048
	global_load_dwordx4 v[128:131], v5, s[48:49] offset:2048
	global_load_dwordx4 v[124:127], v3, s[48:49] offset:3072
	global_load_dwordx4 v[120:123], v5, s[48:49] offset:3072
	global_load_dwordx4 v[116:119], v4, s[48:49] offset:0
	global_load_dwordx4 v[112:115], v213, s[48:49] offset:0
	global_load_dwordx4 v[220:223], v4, s[48:49] offset:1024
	global_load_dwordx4 v[224:227], v213, s[48:49] offset:1024
	global_load_dwordx4 v[228:231], v4, s[48:49] offset:2048
	global_load_dwordx4 v[96:99], v213, s[48:49] offset:2048
	global_load_dwordx4 v[100:103], v4, s[48:49] offset:3072
	global_load_dwordx4 v[104:107], v213, s[48:49] offset:3072
	v_and_b32_e32 v212, 0xffffffc0, v165
	v_lshlrev_b32_e32 v212, 1, v212
	v_lshl_add_u32 v212, v152, 10, v212
	v_lshl_add_u32 v212, v166, 1, v212
	global_load_dwordx2 v[190:191], v212, s[50:51] offset:0
	global_load_dwordx2 v[192:193], v212, s[50:51] offset:16
	global_load_dwordx2 v[194:195], v212, s[50:51] offset:32
	global_load_dwordx2 v[198:199], v212, s[50:51] offset:48
	global_load_dwordx2 v[200:201], v212, s[50:51] offset:64
	global_load_dwordx2 v[202:203], v212, s[50:51] offset:80
	global_load_dwordx2 v[216:217], v212, s[50:51] offset:96
	global_load_dwordx2 v[248:249], v212, s[50:51] offset:112
	v_exp_f32_e32 v80, v80
	v_exp_f32_e32 v81, v81
	v_exp_f32_e32 v82, v82
	v_exp_f32_e32 v83, v83
	v_exp_f32_e32 v84, v84
	v_exp_f32_e32 v85, v85
	v_cvt_pk_bf16_f32 v6, v80, v81
	v_exp_f32_e32 v86, v86
	v_exp_f32_e32 v87, v87
	v_cvt_pk_bf16_f32 v7, v82, v83
	v_cvt_pk_bf16_f32 v8, v84, v85
	v_exp_f32_e32 v88, v88
	v_exp_f32_e32 v89, v89
	v_cvt_pk_bf16_f32 v9, v86, v87
	s_nop 1
	s_waitcnt lgkmcnt(6)
	v_mfma_f32_32x32x16_bf16 v[64:79], v[204:207], v[6:9], v[64:79]
	ds_read_b64_tr_b16 v[204:205], v155 offset:32768
	ds_read_b64_tr_b16 v[206:207], v171 offset:32768
	v_exp_f32_e32 v90, v90
	v_exp_f32_e32 v91, v91
	v_cvt_pk_bf16_f32 v10, v88, v89
	s_waitcnt lgkmcnt(6)
	v_mfma_f32_32x32x16_bf16 v[48:63], v[208:211], v[6:9], v[48:63]
	ds_read_b64_tr_b16 v[208:209], v168 offset:32768
	ds_read_b64_tr_b16 v[210:211], v172 offset:32768
	v_exp_f32_e32 v92, v92
	v_exp_f32_e32 v93, v93
	v_cvt_pk_bf16_f32 v11, v90, v91
	s_waitcnt lgkmcnt(6)
	v_mfma_f32_32x32x16_bf16 v[32:47], v[176:179], v[6:9], v[32:47]
	ds_read_b64_tr_b16 v[176:177], v169 offset:32768
	ds_read_b64_tr_b16 v[178:179], v173 offset:32768
	v_exp_f32_e32 v94, v94
	v_exp_f32_e32 v95, v95
	s_waitcnt lgkmcnt(6)
	v_mfma_f32_32x32x16_bf16 v[16:31], v[184:187], v[6:9], v[16:31]
	ds_read_b64_tr_b16 v[184:185], v170 offset:32768
	ds_read_b64_tr_b16 v[186:187], v174 offset:32768
	v_cvt_pk_bf16_f32 v12, v92, v93
	v_cvt_pk_bf16_f32 v13, v94, v95
	s_nop 1
	s_waitcnt lgkmcnt(6)
	v_mfma_f32_32x32x16_bf16 v[64:79], v[204:207], v[10:13], v[64:79]
	v_add_f32_e32 v175, v175, v80
	v_add_f32_e32 v175, v175, v81
	v_add_f32_e32 v175, v175, v82
	v_add_f32_e32 v175, v175, v83
	s_waitcnt lgkmcnt(4)
	v_mfma_f32_32x32x16_bf16 v[48:63], v[208:211], v[10:13], v[48:63]
	v_add_f32_e32 v175, v175, v84
	v_add_f32_e32 v175, v175, v85
	v_add_f32_e32 v175, v175, v86
	v_add_f32_e32 v175, v175, v87
	s_waitcnt lgkmcnt(2)
	v_mfma_f32_32x32x16_bf16 v[32:47], v[176:179], v[10:13], v[32:47]
	v_add_f32_e32 v175, v175, v88
	v_add_f32_e32 v175, v175, v89
	v_add_f32_e32 v175, v175, v90
	v_add_f32_e32 v175, v175, v91
	s_waitcnt lgkmcnt(0)
	v_mfma_f32_32x32x16_bf16 v[16:31], v[184:187], v[10:13], v[16:31]
	v_add_f32_e32 v175, v175, v92
	v_add_f32_e32 v175, v175, v93
	v_add_f32_e32 v175, v175, v94
	v_add_f32_e32 v175, v175, v95
	s_branch .Lat3_epi_b
.Lat3_tail_c:
	ds_read_b64_tr_b16 v[204:205], v155 offset:49152
	ds_read_b64_tr_b16 v[206:207], v171 offset:49152
	ds_read_b64_tr_b16 v[208:209], v168 offset:49152
	ds_read_b64_tr_b16 v[210:211], v172 offset:49152
	ds_read_b64_tr_b16 v[176:177], v169 offset:49152
	ds_read_b64_tr_b16 v[178:179], v173 offset:49152
	ds_read_b64_tr_b16 v[184:185], v170 offset:49152
	ds_read_b64_tr_b16 v[186:187], v174 offset:49152
	v_and_b32_e32 v3, 63, v165
	v_lshlrev_b32_e32 v3, 4, v3
	v_lshl_add_u32 v3, v154, 14, v3
	v_add_u32_e32 v4, 0x1000, v3
	v_add_u32_e32 v5, 0x2000, v3
	v_add_u32_e32 v213, 0x3000, v3
	global_load_dwordx4 v[148:151], v3, s[48:49] offset:0
	global_load_dwordx4 v[144:147], v5, s[48:49] offset:0
	global_load_dwordx4 v[140:143], v3, s[48:49] offset:1024
	global_load_dwordx4 v[136:139], v5, s[48:49] offset:1024
	global_load_dwordx4 v[132:135], v3, s[48:49] offset:2048
	global_load_dwordx4 v[128:131], v5, s[48:49] offset:2048
	global_load_dwordx4 v[124:127], v3, s[48:49] offset:3072
	global_load_dwordx4 v[120:123], v5, s[48:49] offset:3072
	global_load_dwordx4 v[116:119], v4, s[48:49] offset:0
	global_load_dwordx4 v[112:115], v213, s[48:49] offset:0
	global_load_dwordx4 v[220:223], v4, s[48:49] offset:1024
	global_load_dwordx4 v[224:227], v213, s[48:49] offset:1024
	global_load_dwordx4 v[228:231], v4, s[48:49] offset:2048
	global_load_dwordx4 v[96:99], v213, s[48:49] offset:2048
	global_load_dwordx4 v[100:103], v4, s[48:49] offset:3072
	global_load_dwordx4 v[104:107], v213, s[48:49] offset:3072
	v_and_b32_e32 v212, 0xffffffc0, v165
	v_lshlrev_b32_e32 v212, 1, v212
	v_lshl_add_u32 v212, v152, 10, v212
	v_lshl_add_u32 v212, v166, 1, v212
	global_load_dwordx2 v[190:191], v212, s[50:51] offset:0
	global_load_dwordx2 v[192:193], v212, s[50:51] offset:16
	global_load_dwordx2 v[194:195], v212, s[50:51] offset:32
	global_load_dwordx2 v[198:199], v212, s[50:51] offset:48
	global_load_dwordx2 v[200:201], v212, s[50:51] offset:64
	global_load_dwordx2 v[202:203], v212, s[50:51] offset:80
	global_load_dwordx2 v[216:217], v212, s[50:51] offset:96
	global_load_dwordx2 v[248:249], v212, s[50:51] offset:112
	v_exp_f32_e32 v80, v80
	v_exp_f32_e32 v81, v81
	v_exp_f32_e32 v82, v82
	v_exp_f32_e32 v83, v83
	v_exp_f32_e32 v84, v84
	v_exp_f32_e32 v85, v85
	v_cvt_pk_bf16_f32 v6, v80, v81
	v_exp_f32_e32 v86, v86
	v_exp_f32_e32 v87, v87
	v_cvt_pk_bf16_f32 v7, v82, v83
	v_cvt_pk_bf16_f32 v8, v84, v85
	v_exp_f32_e32 v88, v88
	v_exp_f32_e32 v89, v89
	v_cvt_pk_bf16_f32 v9, v86, v87
	s_nop 1
	s_waitcnt lgkmcnt(6)
	v_mfma_f32_32x32x16_bf16 v[64:79], v[204:207], v[6:9], v[64:79]
	ds_read_b64_tr_b16 v[204:205], v155 offset:53248
	ds_read_b64_tr_b16 v[206:207], v171 offset:53248
	v_exp_f32_e32 v90, v90
	v_exp_f32_e32 v91, v91
	v_cvt_pk_bf16_f32 v10, v88, v89
	s_waitcnt lgkmcnt(6)
	v_mfma_f32_32x32x16_bf16 v[48:63], v[208:211], v[6:9], v[48:63]
	ds_read_b64_tr_b16 v[208:209], v168 offset:53248
	ds_read_b64_tr_b16 v[210:211], v172 offset:53248
	v_exp_f32_e32 v92, v92
	v_exp_f32_e32 v93, v93
	v_cvt_pk_bf16_f32 v11, v90, v91
	s_waitcnt lgkmcnt(6)
	v_mfma_f32_32x32x16_bf16 v[32:47], v[176:179], v[6:9], v[32:47]
	ds_read_b64_tr_b16 v[176:177], v169 offset:53248
	ds_read_b64_tr_b16 v[178:179], v173 offset:53248
	v_exp_f32_e32 v94, v94
	v_exp_f32_e32 v95, v95
	s_waitcnt lgkmcnt(6)
	v_mfma_f32_32x32x16_bf16 v[16:31], v[184:187], v[6:9], v[16:31]
	ds_read_b64_tr_b16 v[184:185], v170 offset:53248
	ds_read_b64_tr_b16 v[186:187], v174 offset:53248
	v_cvt_pk_bf16_f32 v12, v92, v93
	v_cvt_pk_bf16_f32 v13, v94, v95
	s_nop 1
	s_waitcnt lgkmcnt(6)
	v_mfma_f32_32x32x16_bf16 v[64:79], v[204:207], v[10:13], v[64:79]
	v_add_f32_e32 v175, v175, v80
	v_add_f32_e32 v175, v175, v81
	v_add_f32_e32 v175, v175, v82
	v_add_f32_e32 v175, v175, v83
	s_waitcnt lgkmcnt(4)
	v_mfma_f32_32x32x16_bf16 v[48:63], v[208:211], v[10:13], v[48:63]
	v_add_f32_e32 v175, v175, v84
	v_add_f32_e32 v175, v175, v85
	v_add_f32_e32 v175, v175, v86
	v_add_f32_e32 v175, v175, v87
	s_waitcnt lgkmcnt(2)
	v_mfma_f32_32x32x16_bf16 v[32:47], v[176:179], v[10:13], v[32:47]
	v_add_f32_e32 v175, v175, v88
	v_add_f32_e32 v175, v175, v89
	v_add_f32_e32 v175, v175, v90
	v_add_f32_e32 v175, v175, v91
	s_waitcnt lgkmcnt(0)
	v_mfma_f32_32x32x16_bf16 v[16:31], v[184:187], v[10:13], v[16:31]
	v_add_f32_e32 v175, v175, v92
	v_add_f32_e32 v175, v175, v93
	v_add_f32_e32 v175, v175, v94
	v_add_f32_e32 v175, v175, v95
	s_branch .Lat3_epi_b
.Lat3_smp_a:
	ds_read_b64_tr_b16 v[204:205], v155 offset:0
	ds_read_b64_tr_b16 v[206:207], v171 offset:0
	ds_read_b64_tr_b16 v[208:209], v168 offset:0
	ds_read_b64_tr_b16 v[210:211], v172 offset:0
	ds_read_b64_tr_b16 v[176:177], v169 offset:0
	ds_read_b64_tr_b16 v[178:179], v173 offset:0
	ds_read_b64_tr_b16 v[184:185], v170 offset:0
	ds_read_b64_tr_b16 v[186:187], v174 offset:0
	v_and_b32_e32 v3, 63, v165
	v_lshlrev_b32_e32 v3, 4, v3
	v_lshl_add_u32 v3, v154, 14, v3
	v_add_u32_e32 v4, 0x1000, v3
	v_add_u32_e32 v5, 0x2000, v3
	v_add_u32_e32 v213, 0x3000, v3
	global_load_dwordx4 v[148:151], v3, s[48:49] offset:0
	global_load_dwordx4 v[144:147], v5, s[48:49] offset:0
	global_load_dwordx4 v[140:143], v3, s[48:49] offset:1024
	global_load_dwordx4 v[136:139], v5, s[48:49] offset:1024
	global_load_dwordx4 v[132:135], v3, s[48:49] offset:2048
	global_load_dwordx4 v[128:131], v5, s[48:49] offset:2048
	global_load_dwordx4 v[124:127], v3, s[48:49] offset:3072
	global_load_dwordx4 v[120:123], v5, s[48:49] offset:3072
	global_load_dwordx4 v[116:119], v4, s[48:49] offset:0
	global_load_dwordx4 v[112:115], v213, s[48:49] offset:0
	global_load_dwordx4 v[220:223], v4, s[48:49] offset:1024
	global_load_dwordx4 v[224:227], v213, s[48:49] offset:1024
	global_load_dwordx4 v[228:231], v4, s[48:49] offset:2048
	global_load_dwordx4 v[80:83], v213, s[48:49] offset:2048
	global_load_dwordx4 v[84:87], v4, s[48:49] offset:3072
	global_load_dwordx4 v[88:91], v213, s[48:49] offset:3072
	v_and_b32_e32 v212, 0xffffffc0, v165
	v_lshlrev_b32_e32 v212, 1, v212
	v_lshl_add_u32 v212, v152, 10, v212
	v_lshl_add_u32 v212, v166, 1, v212
	global_load_dwordx2 v[190:191], v212, s[50:51] offset:0
	global_load_dwordx2 v[192:193], v212, s[50:51] offset:16
	global_load_dwordx2 v[194:195], v212, s[50:51] offset:32
	global_load_dwordx2 v[198:199], v212, s[50:51] offset:48
	global_load_dwordx2 v[200:201], v212, s[50:51] offset:64
	global_load_dwordx2 v[202:203], v212, s[50:51] offset:80
	global_load_dwordx2 v[216:217], v212, s[50:51] offset:96
	global_load_dwordx2 v[248:249], v212, s[50:51] offset:112
	v_exp_f32_e32 v96, v96
	v_exp_f32_e32 v97, v97
	v_exp_f32_e32 v98, v98
	v_exp_f32_e32 v99, v99
	v_exp_f32_e32 v100, v100
	v_exp_f32_e32 v101, v101
	v_cvt_pk_bf16_f32 v6, v96, v97
	v_exp_f32_e32 v102, v102
	v_exp_f32_e32 v103, v103
	v_cvt_pk_bf16_f32 v7, v98, v99
	v_cvt_pk_bf16_f32 v8, v100, v101
	v_exp_f32_e32 v104, v104
	v_exp_f32_e32 v105, v105
	v_cvt_pk_bf16_f32 v9, v102, v103
	s_nop 1
	s_waitcnt lgkmcnt(6)
	v_mfma_f32_32x32x16_bf16 v[64:79], v[204:207], v[6:9], v[64:79]
	ds_read_b64_tr_b16 v[204:205], v155 offset:4096
	ds_read_b64_tr_b16 v[206:207], v171 offset:4096
	v_exp_f32_e32 v106, v106
	v_exp_f32_e32 v107, v107
	v_cvt_pk_bf16_f32 v10, v104, v105
	s_waitcnt lgkmcnt(6)
	v_mfma_f32_32x32x16_bf16 v[48:63], v[208:211], v[6:9], v[48:63]
	ds_read_b64_tr_b16 v[208:209], v168 offset:4096
	ds_read_b64_tr_b16 v[210:211], v172 offset:4096
	v_exp_f32_e32 v108, v108
	v_exp_f32_e32 v109, v109
	v_cvt_pk_bf16_f32 v11, v106, v107
	s_waitcnt lgkmcnt(6)
	v_mfma_f32_32x32x16_bf16 v[32:47], v[176:179], v[6:9], v[32:47]
	ds_read_b64_tr_b16 v[176:177], v169 offset:4096
	ds_read_b64_tr_b16 v[178:179], v173 offset:4096
	v_exp_f32_e32 v110, v110
	v_exp_f32_e32 v111, v111
	s_waitcnt lgkmcnt(6)
	v_mfma_f32_32x32x16_bf16 v[16:31], v[184:187], v[6:9], v[16:31]
	ds_read_b64_tr_b16 v[184:185], v170 offset:4096
	ds_read_b64_tr_b16 v[186:187], v174 offset:4096
	v_cvt_pk_bf16_f32 v12, v108, v109
	v_cvt_pk_bf16_f32 v13, v110, v111
	s_nop 1
	s_waitcnt lgkmcnt(6)
	v_mfma_f32_32x32x16_bf16 v[64:79], v[204:207], v[10:13], v[64:79]
	v_add_f32_e32 v175, v175, v96
	v_add_f32_e32 v175, v175, v97
	v_add_f32_e32 v175, v175, v98
	v_add_f32_e32 v175, v175, v99
	s_waitcnt lgkmcnt(4)
	v_mfma_f32_32x32x16_bf16 v[48:63], v[208:211], v[10:13], v[48:63]
	v_add_f32_e32 v175, v175, v100
	v_add_f32_e32 v175, v175, v101
	v_add_f32_e32 v175, v175, v102
	v_add_f32_e32 v175, v175, v103
	s_waitcnt lgkmcnt(2)
	v_mfma_f32_32x32x16_bf16 v[32:47], v[176:179], v[10:13], v[32:47]
	v_add_f32_e32 v175, v175, v104
	v_add_f32_e32 v175, v175, v105
	v_add_f32_e32 v175, v175, v106
	v_add_f32_e32 v175, v175, v107
	s_waitcnt lgkmcnt(0)
	v_mfma_f32_32x32x16_bf16 v[16:31], v[184:187], v[10:13], v[16:31]
	v_add_f32_e32 v175, v175, v108
	v_add_f32_e32 v175, v175, v109
	v_add_f32_e32 v175, v175, v110
	v_add_f32_e32 v175, v175, v111
	s_branch .Lat3_epi_a
.Lat3_smp_b:
	ds_read_b64_tr_b16 v[204:205], v155 offset:20480
	ds_read_b64_tr_b16 v[206:207], v171 offset:20480
	ds_read_b64_tr_b16 v[208:209], v168 offset:20480
	ds_read_b64_tr_b16 v[210:211], v172 offset:20480
	ds_read_b64_tr_b16 v[176:177], v169 offset:20480
	ds_read_b64_tr_b16 v[178:179], v173 offset:20480
	ds_read_b64_tr_b16 v[184:185], v170 offset:20480
	ds_read_b64_tr_b16 v[186:187], v174 offset:20480
	v_and_b32_e32 v3, 63, v165
	v_lshlrev_b32_e32 v3, 4, v3
	v_lshl_add_u32 v3, v154, 14, v3
	v_add_u32_e32 v4, 0x1000, v3
	v_add_u32_e32 v5, 0x2000, v3
	v_add_u32_e32 v213, 0x3000, v3
	global_load_dwordx4 v[148:151], v3, s[48:49] offset:0
	global_load_dwordx4 v[144:147], v5, s[48:49] offset:0
	global_load_dwordx4 v[140:143], v3, s[48:49] offset:1024
	global_load_dwordx4 v[136:139], v5, s[48:49] offset:1024
	global_load_dwordx4 v[132:135], v3, s[48:49] offset:2048
	global_load_dwordx4 v[128:131], v5, s[48:49] offset:2048
	global_load_dwordx4 v[124:127], v3, s[48:49] offset:3072
	global_load_dwordx4 v[120:123], v5, s[48:49] offset:3072
	global_load_dwordx4 v[116:119], v4, s[48:49] offset:0
	global_load_dwordx4 v[112:115], v213, s[48:49] offset:0
	global_load_dwordx4 v[220:223], v4, s[48:49] offset:1024
	global_load_dwordx4 v[224:227], v213, s[48:49] offset:1024
	global_load_dwordx4 v[228:231], v4, s[48:49] offset:2048
	global_load_dwordx4 v[80:83], v213, s[48:49] offset:2048
	global_load_dwordx4 v[84:87], v4, s[48:49] offset:3072
	global_load_dwordx4 v[88:91], v213, s[48:49] offset:3072
	v_and_b32_e32 v212, 0xffffffc0, v165
	v_lshlrev_b32_e32 v212, 1, v212
	v_lshl_add_u32 v212, v152, 10, v212
	v_lshl_add_u32 v212, v166, 1, v212
	global_load_dwordx2 v[190:191], v212, s[50:51] offset:0
	global_load_dwordx2 v[192:193], v212, s[50:51] offset:16
	global_load_dwordx2 v[194:195], v212, s[50:51] offset:32
	global_load_dwordx2 v[198:199], v212, s[50:51] offset:48
	global_load_dwordx2 v[200:201], v212, s[50:51] offset:64
	global_load_dwordx2 v[202:203], v212, s[50:51] offset:80
	global_load_dwordx2 v[216:217], v212, s[50:51] offset:96
	global_load_dwordx2 v[248:249], v212, s[50:51] offset:112
	v_exp_f32_e32 v96, v96
	v_exp_f32_e32 v97, v97
	v_exp_f32_e32 v98, v98
	v_exp_f32_e32 v99, v99
	v_exp_f32_e32 v100, v100
	v_exp_f32_e32 v101, v101
	v_cvt_pk_bf16_f32 v6, v96, v97
	v_exp_f32_e32 v102, v102
	v_exp_f32_e32 v103, v103
	v_cvt_pk_bf16_f32 v7, v98, v99
	v_cvt_pk_bf16_f32 v8, v100, v101
	v_exp_f32_e32 v104, v104
	v_exp_f32_e32 v105, v105
	v_cvt_pk_bf16_f32 v9, v102, v103
	s_nop 1
	s_waitcnt lgkmcnt(6)
	v_mfma_f32_32x32x16_bf16 v[64:79], v[204:207], v[6:9], v[64:79]
	ds_read_b64_tr_b16 v[204:205], v155 offset:24576
	ds_read_b64_tr_b16 v[206:207], v171 offset:24576
	v_exp_f32_e32 v106, v106
	v_exp_f32_e32 v107, v107
	v_cvt_pk_bf16_f32 v10, v104, v105
	s_waitcnt lgkmcnt(6)
	v_mfma_f32_32x32x16_bf16 v[48:63], v[208:211], v[6:9], v[48:63]
	ds_read_b64_tr_b16 v[208:209], v168 offset:24576
	ds_read_b64_tr_b16 v[210:211], v172 offset:24576
	v_exp_f32_e32 v108, v108
	v_exp_f32_e32 v109, v109
	v_cvt_pk_bf16_f32 v11, v106, v107
	s_waitcnt lgkmcnt(6)
	v_mfma_f32_32x32x16_bf16 v[32:47], v[176:179], v[6:9], v[32:47]
	ds_read_b64_tr_b16 v[176:177], v169 offset:24576
	ds_read_b64_tr_b16 v[178:179], v173 offset:24576
	v_exp_f32_e32 v110, v110
	v_exp_f32_e32 v111, v111
	s_waitcnt lgkmcnt(6)
	v_mfma_f32_32x32x16_bf16 v[16:31], v[184:187], v[6:9], v[16:31]
	ds_read_b64_tr_b16 v[184:185], v170 offset:24576
	ds_read_b64_tr_b16 v[186:187], v174 offset:24576
	v_cvt_pk_bf16_f32 v12, v108, v109
	v_cvt_pk_bf16_f32 v13, v110, v111
	s_nop 1
	s_waitcnt lgkmcnt(6)
	v_mfma_f32_32x32x16_bf16 v[64:79], v[204:207], v[10:13], v[64:79]
	v_add_f32_e32 v175, v175, v96
	v_add_f32_e32 v175, v175, v97
	v_add_f32_e32 v175, v175, v98
	v_add_f32_e32 v175, v175, v99
	s_waitcnt lgkmcnt(4)
	v_mfma_f32_32x32x16_bf16 v[48:63], v[208:211], v[10:13], v[48:63]
	v_add_f32_e32 v175, v175, v100
	v_add_f32_e32 v175, v175, v101
	v_add_f32_e32 v175, v175, v102
	v_add_f32_e32 v175, v175, v103
	s_waitcnt lgkmcnt(2)
	v_mfma_f32_32x32x16_bf16 v[32:47], v[176:179], v[10:13], v[32:47]
	v_add_f32_e32 v175, v175, v104
	v_add_f32_e32 v175, v175, v105
	v_add_f32_e32 v175, v175, v106
	v_add_f32_e32 v175, v175, v107
	s_waitcnt lgkmcnt(0)
	v_mfma_f32_32x32x16_bf16 v[16:31], v[184:187], v[10:13], v[16:31]
	v_add_f32_e32 v175, v175, v108
	v_add_f32_e32 v175, v175, v109
	v_add_f32_e32 v175, v175, v110
	v_add_f32_e32 v175, v175, v111
	s_branch .Lat3_epi_a
.Lat3_smp_c:
	ds_read_b64_tr_b16 v[204:205], v155 offset:40960
	ds_read_b64_tr_b16 v[206:207], v171 offset:40960
	ds_read_b64_tr_b16 v[208:209], v168 offset:40960
	ds_read_b64_tr_b16 v[210:211], v172 offset:40960
	ds_read_b64_tr_b16 v[176:177], v169 offset:40960
	ds_read_b64_tr_b16 v[178:179], v173 offset:40960
	ds_read_b64_tr_b16 v[184:185], v170 offset:40960
	ds_read_b64_tr_b16 v[186:187], v174 offset:40960
	v_and_b32_e32 v3, 63, v165
	v_lshlrev_b32_e32 v3, 4, v3
	v_lshl_add_u32 v3, v154, 14, v3
	v_add_u32_e32 v4, 0x1000, v3
	v_add_u32_e32 v5, 0x2000, v3
	v_add_u32_e32 v213, 0x3000, v3
	global_load_dwordx4 v[148:151], v3, s[48:49] offset:0
	global_load_dwordx4 v[144:147], v5, s[48:49] offset:0
	global_load_dwordx4 v[140:143], v3, s[48:49] offset:1024
	global_load_dwordx4 v[136:139], v5, s[48:49] offset:1024
	global_load_dwordx4 v[132:135], v3, s[48:49] offset:2048
	global_load_dwordx4 v[128:131], v5, s[48:49] offset:2048
	global_load_dwordx4 v[124:127], v3, s[48:49] offset:3072
	global_load_dwordx4 v[120:123], v5, s[48:49] offset:3072
	global_load_dwordx4 v[116:119], v4, s[48:49] offset:0
	global_load_dwordx4 v[112:115], v213, s[48:49] offset:0
	global_load_dwordx4 v[220:223], v4, s[48:49] offset:1024
	global_load_dwordx4 v[224:227], v213, s[48:49] offset:1024
	global_load_dwordx4 v[228:231], v4, s[48:49] offset:2048
	global_load_dwordx4 v[80:83], v213, s[48:49] offset:2048
	global_load_dwordx4 v[84:87], v4, s[48:49] offset:3072
	global_load_dwordx4 v[88:91], v213, s[48:49] offset:3072
	v_and_b32_e32 v212, 0xffffffc0, v165
	v_lshlrev_b32_e32 v212, 1, v212
	v_lshl_add_u32 v212, v152, 10, v212
	v_lshl_add_u32 v212, v166, 1, v212
	global_load_dwordx2 v[190:191], v212, s[50:51] offset:0
	global_load_dwordx2 v[192:193], v212, s[50:51] offset:16
	global_load_dwordx2 v[194:195], v212, s[50:51] offset:32
	global_load_dwordx2 v[198:199], v212, s[50:51] offset:48
	global_load_dwordx2 v[200:201], v212, s[50:51] offset:64
	global_load_dwordx2 v[202:203], v212, s[50:51] offset:80
	global_load_dwordx2 v[216:217], v212, s[50:51] offset:96
	global_load_dwordx2 v[248:249], v212, s[50:51] offset:112
	v_exp_f32_e32 v96, v96
	v_exp_f32_e32 v97, v97
	v_exp_f32_e32 v98, v98
	v_exp_f32_e32 v99, v99
	v_exp_f32_e32 v100, v100
	v_exp_f32_e32 v101, v101
	v_cvt_pk_bf16_f32 v6, v96, v97
	v_exp_f32_e32 v102, v102
	v_exp_f32_e32 v103, v103
	v_cvt_pk_bf16_f32 v7, v98, v99
	v_cvt_pk_bf16_f32 v8, v100, v101
	v_exp_f32_e32 v104, v104
	v_exp_f32_e32 v105, v105
	v_cvt_pk_bf16_f32 v9, v102, v103
	s_nop 1
	s_waitcnt lgkmcnt(6)
	v_mfma_f32_32x32x16_bf16 v[64:79], v[204:207], v[6:9], v[64:79]
	ds_read_b64_tr_b16 v[204:205], v155 offset:45056
	ds_read_b64_tr_b16 v[206:207], v171 offset:45056
	v_exp_f32_e32 v106, v106
	v_exp_f32_e32 v107, v107
	v_cvt_pk_bf16_f32 v10, v104, v105
	s_waitcnt lgkmcnt(6)
	v_mfma_f32_32x32x16_bf16 v[48:63], v[208:211], v[6:9], v[48:63]
	ds_read_b64_tr_b16 v[208:209], v168 offset:45056
	ds_read_b64_tr_b16 v[210:211], v172 offset:45056
	v_exp_f32_e32 v108, v108
	v_exp_f32_e32 v109, v109
	v_cvt_pk_bf16_f32 v11, v106, v107
	s_waitcnt lgkmcnt(6)
	v_mfma_f32_32x32x16_bf16 v[32:47], v[176:179], v[6:9], v[32:47]
	ds_read_b64_tr_b16 v[176:177], v169 offset:45056
	ds_read_b64_tr_b16 v[178:179], v173 offset:45056
	v_exp_f32_e32 v110, v110
	v_exp_f32_e32 v111, v111
	s_waitcnt lgkmcnt(6)
	v_mfma_f32_32x32x16_bf16 v[16:31], v[184:187], v[6:9], v[16:31]
	ds_read_b64_tr_b16 v[184:185], v170 offset:45056
	ds_read_b64_tr_b16 v[186:187], v174 offset:45056
	v_cvt_pk_bf16_f32 v12, v108, v109
	v_cvt_pk_bf16_f32 v13, v110, v111
	s_nop 1
	s_waitcnt lgkmcnt(6)
	v_mfma_f32_32x32x16_bf16 v[64:79], v[204:207], v[10:13], v[64:79]
	v_add_f32_e32 v175, v175, v96
	v_add_f32_e32 v175, v175, v97
	v_add_f32_e32 v175, v175, v98
	v_add_f32_e32 v175, v175, v99
	s_waitcnt lgkmcnt(4)
	v_mfma_f32_32x32x16_bf16 v[48:63], v[208:211], v[10:13], v[48:63]
	v_add_f32_e32 v175, v175, v100
	v_add_f32_e32 v175, v175, v101
	v_add_f32_e32 v175, v175, v102
	v_add_f32_e32 v175, v175, v103
	s_waitcnt lgkmcnt(2)
	v_mfma_f32_32x32x16_bf16 v[32:47], v[176:179], v[10:13], v[32:47]
	v_add_f32_e32 v175, v175, v104
	v_add_f32_e32 v175, v175, v105
	v_add_f32_e32 v175, v175, v106
	v_add_f32_e32 v175, v175, v107
	s_waitcnt lgkmcnt(0)
	v_mfma_f32_32x32x16_bf16 v[16:31], v[184:187], v[10:13], v[16:31]
	v_add_f32_e32 v175, v175, v108
	v_add_f32_e32 v175, v175, v109
	v_add_f32_e32 v175, v175, v110
	v_add_f32_e32 v175, v175, v111
	s_branch .Lat3_epi_a
.Lat3_epi_b:
	v_mov_b32_e32 v15, v175
	s_nop 1
	v_permlane32_swap_b32_e32 v175, v15
	v_add_f32_e32 v175, v175, v15
	v_div_scale_f32 v2, s[16:17], v175, v175, 1.0
	v_div_scale_f32 v4, vcc, 1.0, v175, 1.0
	v_rcp_f32_e32 v3, v2
	s_nop 1
	v_fma_f32 v5, -v2, v3, 1.0
	v_fmac_f32_e32 v3, v5, v3
	v_mul_f32_e32 v5, v4, v3
	v_fma_f32 v213, -v2, v5, v4
	v_fmac_f32_e32 v5, v213, v3
	v_fma_f32 v2, -v2, v5, v4
	v_div_fmas_f32 v2, v2, v3, v5
	v_div_fixup_f32 v0, v2, v175, 1.0
	s_nop 4
	v_mul_f32_e32 v64, v64, v0
	v_mul_f32_e32 v65, v65, v0
	v_mul_f32_e32 v66, v66, v0
	v_mul_f32_e32 v67, v67, v0
	v_mul_f32_e32 v68, v68, v0
	v_mul_f32_e32 v69, v69, v0
	v_mul_f32_e32 v70, v70, v0
	v_mul_f32_e32 v71, v71, v0
	v_cvt_pk_bf16_f32 v6, v64, v65
	v_cvt_pk_bf16_f32 v7, v66, v67
	v_cvt_pk_bf16_f32 v8, v68, v69
	v_cvt_pk_bf16_f32 v9, v70, v71
	s_nop 1
	s_waitcnt vmcnt(23)
	v_mfma_f32_32x32x16_bf16 v[232:247], v[148:151], v[6:9], 0
	s_waitcnt vmcnt(22)
	v_mfma_f32_32x32x16_bf16 v[80:95], v[144:147], v[6:9], 0
	v_mul_f32_e32 v72, v72, v0
	v_mul_f32_e32 v73, v73, v0
	v_mul_f32_e32 v74, v74, v0
	v_mul_f32_e32 v75, v75, v0
	v_mul_f32_e32 v76, v76, v0
	v_mul_f32_e32 v77, v77, v0
	v_mul_f32_e32 v78, v78, v0
	v_mul_f32_e32 v79, v79, v0
	v_cvt_pk_bf16_f32 v10, v72, v73
	v_cvt_pk_bf16_f32 v11, v74, v75
	v_cvt_pk_bf16_f32 v12, v76, v77
	v_cvt_pk_bf16_f32 v13, v78, v79
	s_nop 1
	s_waitcnt vmcnt(21)
	v_mfma_f32_32x32x16_bf16 v[232:247], v[140:143], v[10:13], v[232:247]
	s_waitcnt vmcnt(20)
	v_mfma_f32_32x32x16_bf16 v[80:95], v[136:139], v[10:13], v[80:95]
	v_mul_f32_e32 v48, v48, v0
	v_mul_f32_e32 v49, v49, v0
	v_mul_f32_e32 v50, v50, v0
	v_mul_f32_e32 v51, v51, v0
	v_mul_f32_e32 v52, v52, v0
	v_mul_f32_e32 v53, v53, v0
	v_mul_f32_e32 v54, v54, v0
	v_mul_f32_e32 v55, v55, v0
	v_cvt_pk_bf16_f32 v6, v48, v49
	v_cvt_pk_bf16_f32 v7, v50, v51
	v_cvt_pk_bf16_f32 v8, v52, v53
	v_cvt_pk_bf16_f32 v9, v54, v55
	s_nop 1
	s_waitcnt vmcnt(19)
	v_mfma_f32_32x32x16_bf16 v[232:247], v[132:135], v[6:9], v[232:247]
	s_waitcnt vmcnt(18)
	v_mfma_f32_32x32x16_bf16 v[80:95], v[128:131], v[6:9], v[80:95]
	v_mul_f32_e32 v56, v56, v0
	v_mul_f32_e32 v57, v57, v0
	v_mul_f32_e32 v58, v58, v0
	v_mul_f32_e32 v59, v59, v0
	v_mul_f32_e32 v60, v60, v0
	v_mul_f32_e32 v61, v61, v0
	v_mul_f32_e32 v62, v62, v0
	v_mul_f32_e32 v63, v63, v0
	v_cvt_pk_bf16_f32 v10, v56, v57
	v_cvt_pk_bf16_f32 v11, v58, v59
	v_cvt_pk_bf16_f32 v12, v60, v61
	v_cvt_pk_bf16_f32 v13, v62, v63
	s_nop 1
	s_waitcnt vmcnt(17)
	v_mfma_f32_32x32x16_bf16 v[232:247], v[124:127], v[10:13], v[232:247]
	s_waitcnt vmcnt(16)
	v_mfma_f32_32x32x16_bf16 v[80:95], v[120:123], v[10:13], v[80:95]
	v_mul_f32_e32 v32, v32, v0
	v_mul_f32_e32 v33, v33, v0
	v_mul_f32_e32 v34, v34, v0
	v_mul_f32_e32 v35, v35, v0
	v_mul_f32_e32 v36, v36, v0
	v_mul_f32_e32 v37, v37, v0
	v_mul_f32_e32 v38, v38, v0
	v_mul_f32_e32 v39, v39, v0
	v_cvt_pk_bf16_f32 v6, v32, v33
	v_cvt_pk_bf16_f32 v7, v34, v35
	v_cvt_pk_bf16_f32 v8, v36, v37
	v_cvt_pk_bf16_f32 v9, v38, v39
	s_nop 1
	s_waitcnt vmcnt(15)
	v_mfma_f32_32x32x16_bf16 v[232:247], v[116:119], v[6:9], v[232:247]
	s_waitcnt vmcnt(14)
	v_mfma_f32_32x32x16_bf16 v[80:95], v[112:115], v[6:9], v[80:95]
	v_mul_f32_e32 v40, v40, v0
	v_mul_f32_e32 v41, v41, v0
	v_mul_f32_e32 v42, v42, v0
	v_mul_f32_e32 v43, v43, v0
	v_mul_f32_e32 v44, v44, v0
	v_mul_f32_e32 v45, v45, v0
	v_mul_f32_e32 v46, v46, v0
	v_mul_f32_e32 v47, v47, v0
	v_cvt_pk_bf16_f32 v10, v40, v41
	v_cvt_pk_bf16_f32 v11, v42, v43
	v_cvt_pk_bf16_f32 v12, v44, v45
	v_cvt_pk_bf16_f32 v13, v46, v47
	s_nop 1
	s_waitcnt vmcnt(13)
	v_mfma_f32_32x32x16_bf16 v[232:247], v[220:223], v[10:13], v[232:247]
	s_waitcnt vmcnt(12)
	v_mfma_f32_32x32x16_bf16 v[80:95], v[224:227], v[10:13], v[80:95]
	v_mul_f32_e32 v16, v16, v0
	v_mul_f32_e32 v17, v17, v0
	v_mul_f32_e32 v18, v18, v0
	v_mul_f32_e32 v19, v19, v0
	v_mul_f32_e32 v20, v20, v0
	v_mul_f32_e32 v21, v21, v0
	v_mul_f32_e32 v22, v22, v0
	v_mul_f32_e32 v23, v23, v0
	v_cvt_pk_bf16_f32 v6, v16, v17
	v_cvt_pk_bf16_f32 v7, v18, v19
	v_cvt_pk_bf16_f32 v8, v20, v21
	v_cvt_pk_bf16_f32 v9, v22, v23
	s_nop 1
	s_waitcnt vmcnt(11)
	v_mfma_f32_32x32x16_bf16 v[232:247], v[228:231], v[6:9], v[232:247]
	s_waitcnt vmcnt(10)
	v_mfma_f32_32x32x16_bf16 v[80:95], v[96:99], v[6:9], v[80:95]
	v_mul_f32_e32 v24, v24, v0
	v_mul_f32_e32 v25, v25, v0
	v_mul_f32_e32 v26, v26, v0
	v_mul_f32_e32 v27, v27, v0
	v_mul_f32_e32 v28, v28, v0
	v_mul_f32_e32 v29, v29, v0
	v_mul_f32_e32 v30, v30, v0
	v_mul_f32_e32 v31, v31, v0
	v_cvt_pk_bf16_f32 v10, v24, v25
	v_cvt_pk_bf16_f32 v11, v26, v27
	v_cvt_pk_bf16_f32 v12, v28, v29
	v_cvt_pk_bf16_f32 v13, v30, v31
	s_nop 1
	s_waitcnt vmcnt(9)
	v_mfma_f32_32x32x16_bf16 v[232:247], v[100:103], v[10:13], v[232:247]
	s_waitcnt vmcnt(8)
	v_mfma_f32_32x32x16_bf16 v[80:95], v[104:107], v[10:13], v[80:95]
	v_cmp_gt_u32_e32 vcc, s76, v167
	s_and_saveexec_b64 s[6:7], vcc
	s_cbranch_execz .LBB0_470
	s_nop 10
	s_waitcnt vmcnt(7)
	v_lshlrev_b32_e32 v2, 16, v190
	v_and_b32_e32 v3, 0xffff0000, v190
	v_lshlrev_b32_e32 v4, 16, v191
	v_and_b32_e32 v5, 0xffff0000, v191
	v_mul_f32_e32 v232, v232, v2
	v_mul_f32_e32 v233, v233, v3
	v_mul_f32_e32 v234, v234, v4
	v_mul_f32_e32 v235, v235, v5
	v_cvt_pk_bf16_f32 v190, v232, v233
	v_cvt_pk_bf16_f32 v191, v234, v235
	s_waitcnt vmcnt(6)
	v_lshlrev_b32_e32 v2, 16, v192
	v_and_b32_e32 v3, 0xffff0000, v192
	v_lshlrev_b32_e32 v4, 16, v193
	v_and_b32_e32 v5, 0xffff0000, v193
	v_mul_f32_e32 v236, v236, v2
	v_mul_f32_e32 v237, v237, v3
	v_mul_f32_e32 v238, v238, v4
	v_mul_f32_e32 v239, v239, v5
	v_cvt_pk_bf16_f32 v192, v236, v237
	v_cvt_pk_bf16_f32 v193, v238, v239
	s_waitcnt vmcnt(5)
	v_lshlrev_b32_e32 v2, 16, v194
	v_and_b32_e32 v3, 0xffff0000, v194
	v_lshlrev_b32_e32 v4, 16, v195
	v_and_b32_e32 v5, 0xffff0000, v195
	v_mul_f32_e32 v240, v240, v2
	v_mul_f32_e32 v241, v241, v3
	v_mul_f32_e32 v242, v242, v4
	v_mul_f32_e32 v243, v243, v5
	v_cvt_pk_bf16_f32 v194, v240, v241
	v_cvt_pk_bf16_f32 v195, v242, v243
	s_waitcnt vmcnt(4)
	v_lshlrev_b32_e32 v2, 16, v198
	v_and_b32_e32 v3, 0xffff0000, v198
	v_lshlrev_b32_e32 v4, 16, v199
	v_and_b32_e32 v5, 0xffff0000, v199
	v_mul_f32_e32 v244, v244, v2
	v_mul_f32_e32 v245, v245, v3
	v_mul_f32_e32 v246, v246, v4
	v_mul_f32_e32 v247, v247, v5
	v_cvt_pk_bf16_f32 v198, v244, v245
	v_cvt_pk_bf16_f32 v199, v246, v247
	s_waitcnt vmcnt(3)
	v_lshlrev_b32_e32 v2, 16, v200
	v_and_b32_e32 v3, 0xffff0000, v200
	v_lshlrev_b32_e32 v4, 16, v201
	v_and_b32_e32 v5, 0xffff0000, v201
	v_mul_f32_e32 v80, v80, v2
	v_mul_f32_e32 v81, v81, v3
	v_mul_f32_e32 v82, v82, v4
	v_mul_f32_e32 v83, v83, v5
	v_cvt_pk_bf16_f32 v200, v80, v81
	v_cvt_pk_bf16_f32 v201, v82, v83
	s_waitcnt vmcnt(2)
	v_lshlrev_b32_e32 v2, 16, v202
	v_and_b32_e32 v3, 0xffff0000, v202
	v_lshlrev_b32_e32 v4, 16, v203
	v_and_b32_e32 v5, 0xffff0000, v203
	v_mul_f32_e32 v84, v84, v2
	v_mul_f32_e32 v85, v85, v3
	v_mul_f32_e32 v86, v86, v4
	v_mul_f32_e32 v87, v87, v5
	v_cvt_pk_bf16_f32 v202, v84, v85
	v_cvt_pk_bf16_f32 v203, v86, v87
	s_waitcnt vmcnt(1)
	v_lshlrev_b32_e32 v2, 16, v216
	v_and_b32_e32 v3, 0xffff0000, v216
	v_lshlrev_b32_e32 v4, 16, v217
	v_and_b32_e32 v5, 0xffff0000, v217
	v_mul_f32_e32 v88, v88, v2
	v_mul_f32_e32 v89, v89, v3
	v_mul_f32_e32 v90, v90, v4
	v_mul_f32_e32 v91, v91, v5
	v_cvt_pk_bf16_f32 v216, v88, v89
	v_cvt_pk_bf16_f32 v217, v90, v91
	s_waitcnt vmcnt(0)
	v_lshlrev_b32_e32 v2, 16, v248
	v_and_b32_e32 v3, 0xffff0000, v248
	v_lshlrev_b32_e32 v4, 16, v249
	v_and_b32_e32 v5, 0xffff0000, v249
	v_mul_f32_e32 v92, v92, v2
	v_mul_f32_e32 v93, v93, v3
	v_mul_f32_e32 v94, v94, v4
	v_mul_f32_e32 v95, v95, v5
	v_cvt_pk_bf16_f32 v248, v92, v93
	v_cvt_pk_bf16_f32 v249, v94, v95
	global_store_dwordx2 v212, v[190:191], s[52:53] offset:0
	global_store_dwordx2 v212, v[192:193], s[52:53] offset:16
	global_store_dwordx2 v212, v[194:195], s[52:53] offset:32
	global_store_dwordx2 v212, v[198:199], s[52:53] offset:48
	global_store_dwordx2 v212, v[200:201], s[52:53] offset:64
	global_store_dwordx2 v212, v[202:203], s[52:53] offset:80
	global_store_dwordx2 v212, v[216:217], s[52:53] offset:96
	global_store_dwordx2 v212, v[248:249], s[52:53] offset:112
	s_branch .LBB0_470
.Lat3_epi_a:
	v_mov_b32_e32 v15, v175
	s_nop 1
	v_permlane32_swap_b32_e32 v175, v15
	v_add_f32_e32 v175, v175, v15
	v_div_scale_f32 v2, s[16:17], v175, v175, 1.0
	v_div_scale_f32 v4, vcc, 1.0, v175, 1.0
	v_rcp_f32_e32 v3, v2
	s_nop 1
	v_fma_f32 v5, -v2, v3, 1.0
	v_fmac_f32_e32 v3, v5, v3
	v_mul_f32_e32 v5, v4, v3
	v_fma_f32 v213, -v2, v5, v4
	v_fmac_f32_e32 v5, v213, v3
	v_fma_f32 v2, -v2, v5, v4
	v_div_fmas_f32 v2, v2, v3, v5
	v_div_fixup_f32 v0, v2, v175, 1.0
	s_nop 4
	v_mul_f32_e32 v64, v64, v0
	v_mul_f32_e32 v65, v65, v0
	v_mul_f32_e32 v66, v66, v0
	v_mul_f32_e32 v67, v67, v0
	v_mul_f32_e32 v68, v68, v0
	v_mul_f32_e32 v69, v69, v0
	v_mul_f32_e32 v70, v70, v0
	v_mul_f32_e32 v71, v71, v0
	v_cvt_pk_bf16_f32 v6, v64, v65
	v_cvt_pk_bf16_f32 v7, v66, v67
	v_cvt_pk_bf16_f32 v8, v68, v69
	v_cvt_pk_bf16_f32 v9, v70, v71
	s_nop 1
	s_waitcnt vmcnt(23)
	v_mfma_f32_32x32x16_bf16 v[232:247], v[148:151], v[6:9], 0
	s_waitcnt vmcnt(22)
	v_mfma_f32_32x32x16_bf16 v[96:111], v[144:147], v[6:9], 0
	v_mul_f32_e32 v72, v72, v0
	v_mul_f32_e32 v73, v73, v0
	v_mul_f32_e32 v74, v74, v0
	v_mul_f32_e32 v75, v75, v0
	v_mul_f32_e32 v76, v76, v0
	v_mul_f32_e32 v77, v77, v0
	v_mul_f32_e32 v78, v78, v0
	v_mul_f32_e32 v79, v79, v0
	v_cvt_pk_bf16_f32 v10, v72, v73
	v_cvt_pk_bf16_f32 v11, v74, v75
	v_cvt_pk_bf16_f32 v12, v76, v77
	v_cvt_pk_bf16_f32 v13, v78, v79
	s_nop 1
	s_waitcnt vmcnt(21)
	v_mfma_f32_32x32x16_bf16 v[232:247], v[140:143], v[10:13], v[232:247]
	s_waitcnt vmcnt(20)
	v_mfma_f32_32x32x16_bf16 v[96:111], v[136:139], v[10:13], v[96:111]
	v_mul_f32_e32 v48, v48, v0
	v_mul_f32_e32 v49, v49, v0
	v_mul_f32_e32 v50, v50, v0
	v_mul_f32_e32 v51, v51, v0
	v_mul_f32_e32 v52, v52, v0
	v_mul_f32_e32 v53, v53, v0
	v_mul_f32_e32 v54, v54, v0
	v_mul_f32_e32 v55, v55, v0
	v_cvt_pk_bf16_f32 v6, v48, v49
	v_cvt_pk_bf16_f32 v7, v50, v51
	v_cvt_pk_bf16_f32 v8, v52, v53
	v_cvt_pk_bf16_f32 v9, v54, v55
	s_nop 1
	s_waitcnt vmcnt(19)
	v_mfma_f32_32x32x16_bf16 v[232:247], v[132:135], v[6:9], v[232:247]
	s_waitcnt vmcnt(18)
	v_mfma_f32_32x32x16_bf16 v[96:111], v[128:131], v[6:9], v[96:111]
	v_mul_f32_e32 v56, v56, v0
	v_mul_f32_e32 v57, v57, v0
	v_mul_f32_e32 v58, v58, v0
	v_mul_f32_e32 v59, v59, v0
	v_mul_f32_e32 v60, v60, v0
	v_mul_f32_e32 v61, v61, v0
	v_mul_f32_e32 v62, v62, v0
	v_mul_f32_e32 v63, v63, v0
	v_cvt_pk_bf16_f32 v10, v56, v57
	v_cvt_pk_bf16_f32 v11, v58, v59
	v_cvt_pk_bf16_f32 v12, v60, v61
	v_cvt_pk_bf16_f32 v13, v62, v63
	s_nop 1
	s_waitcnt vmcnt(17)
	v_mfma_f32_32x32x16_bf16 v[232:247], v[124:127], v[10:13], v[232:247]
	s_waitcnt vmcnt(16)
	v_mfma_f32_32x32x16_bf16 v[96:111], v[120:123], v[10:13], v[96:111]
	v_mul_f32_e32 v32, v32, v0
	v_mul_f32_e32 v33, v33, v0
	v_mul_f32_e32 v34, v34, v0
	v_mul_f32_e32 v35, v35, v0
	v_mul_f32_e32 v36, v36, v0
	v_mul_f32_e32 v37, v37, v0
	v_mul_f32_e32 v38, v38, v0
	v_mul_f32_e32 v39, v39, v0
	v_cvt_pk_bf16_f32 v6, v32, v33
	v_cvt_pk_bf16_f32 v7, v34, v35
	v_cvt_pk_bf16_f32 v8, v36, v37
	v_cvt_pk_bf16_f32 v9, v38, v39
	s_nop 1
	s_waitcnt vmcnt(15)
	v_mfma_f32_32x32x16_bf16 v[232:247], v[116:119], v[6:9], v[232:247]
	s_waitcnt vmcnt(14)
	v_mfma_f32_32x32x16_bf16 v[96:111], v[112:115], v[6:9], v[96:111]
	v_mul_f32_e32 v40, v40, v0
	v_mul_f32_e32 v41, v41, v0
	v_mul_f32_e32 v42, v42, v0
	v_mul_f32_e32 v43, v43, v0
	v_mul_f32_e32 v44, v44, v0
	v_mul_f32_e32 v45, v45, v0
	v_mul_f32_e32 v46, v46, v0
	v_mul_f32_e32 v47, v47, v0
	v_cvt_pk_bf16_f32 v10, v40, v41
	v_cvt_pk_bf16_f32 v11, v42, v43
	v_cvt_pk_bf16_f32 v12, v44, v45
	v_cvt_pk_bf16_f32 v13, v46, v47
	s_nop 1
	s_waitcnt vmcnt(13)
	v_mfma_f32_32x32x16_bf16 v[232:247], v[220:223], v[10:13], v[232:247]
	s_waitcnt vmcnt(12)
	v_mfma_f32_32x32x16_bf16 v[96:111], v[224:227], v[10:13], v[96:111]
	v_mul_f32_e32 v16, v16, v0
	v_mul_f32_e32 v17, v17, v0
	v_mul_f32_e32 v18, v18, v0
	v_mul_f32_e32 v19, v19, v0
	v_mul_f32_e32 v20, v20, v0
	v_mul_f32_e32 v21, v21, v0
	v_mul_f32_e32 v22, v22, v0
	v_mul_f32_e32 v23, v23, v0
	v_cvt_pk_bf16_f32 v6, v16, v17
	v_cvt_pk_bf16_f32 v7, v18, v19
	v_cvt_pk_bf16_f32 v8, v20, v21
	v_cvt_pk_bf16_f32 v9, v22, v23
	s_nop 1
	s_waitcnt vmcnt(11)
	v_mfma_f32_32x32x16_bf16 v[232:247], v[228:231], v[6:9], v[232:247]
	s_waitcnt vmcnt(10)
	v_mfma_f32_32x32x16_bf16 v[96:111], v[80:83], v[6:9], v[96:111]
	v_mul_f32_e32 v24, v24, v0
	v_mul_f32_e32 v25, v25, v0
	v_mul_f32_e32 v26, v26, v0
	v_mul_f32_e32 v27, v27, v0
	v_mul_f32_e32 v28, v28, v0
	v_mul_f32_e32 v29, v29, v0
	v_mul_f32_e32 v30, v30, v0
	v_mul_f32_e32 v31, v31, v0
	v_cvt_pk_bf16_f32 v10, v24, v25
	v_cvt_pk_bf16_f32 v11, v26, v27
	v_cvt_pk_bf16_f32 v12, v28, v29
	v_cvt_pk_bf16_f32 v13, v30, v31
	s_nop 1
	s_waitcnt vmcnt(9)
	v_mfma_f32_32x32x16_bf16 v[232:247], v[84:87], v[10:13], v[232:247]
	s_waitcnt vmcnt(8)
	v_mfma_f32_32x32x16_bf16 v[96:111], v[88:91], v[10:13], v[96:111]
	v_cmp_gt_u32_e32 vcc, s76, v167
	s_and_saveexec_b64 s[6:7], vcc
	s_cbranch_execz .LBB0_470
	s_nop 10
	s_waitcnt vmcnt(7)
	v_lshlrev_b32_e32 v2, 16, v190
	v_and_b32_e32 v3, 0xffff0000, v190
	v_lshlrev_b32_e32 v4, 16, v191
	v_and_b32_e32 v5, 0xffff0000, v191
	v_mul_f32_e32 v232, v232, v2
	v_mul_f32_e32 v233, v233, v3
	v_mul_f32_e32 v234, v234, v4
	v_mul_f32_e32 v235, v235, v5
	v_cvt_pk_bf16_f32 v190, v232, v233
	v_cvt_pk_bf16_f32 v191, v234, v235
	s_waitcnt vmcnt(6)
	v_lshlrev_b32_e32 v2, 16, v192
	v_and_b32_e32 v3, 0xffff0000, v192
	v_lshlrev_b32_e32 v4, 16, v193
	v_and_b32_e32 v5, 0xffff0000, v193
	v_mul_f32_e32 v236, v236, v2
	v_mul_f32_e32 v237, v237, v3
	v_mul_f32_e32 v238, v238, v4
	v_mul_f32_e32 v239, v239, v5
	v_cvt_pk_bf16_f32 v192, v236, v237
	v_cvt_pk_bf16_f32 v193, v238, v239
	s_waitcnt vmcnt(5)
	v_lshlrev_b32_e32 v2, 16, v194
	v_and_b32_e32 v3, 0xffff0000, v194
	v_lshlrev_b32_e32 v4, 16, v195
	v_and_b32_e32 v5, 0xffff0000, v195
	v_mul_f32_e32 v240, v240, v2
	v_mul_f32_e32 v241, v241, v3
	v_mul_f32_e32 v242, v242, v4
	v_mul_f32_e32 v243, v243, v5
	v_cvt_pk_bf16_f32 v194, v240, v241
	v_cvt_pk_bf16_f32 v195, v242, v243
	s_waitcnt vmcnt(4)
	v_lshlrev_b32_e32 v2, 16, v198
	v_and_b32_e32 v3, 0xffff0000, v198
	v_lshlrev_b32_e32 v4, 16, v199
	v_and_b32_e32 v5, 0xffff0000, v199
	v_mul_f32_e32 v244, v244, v2
	v_mul_f32_e32 v245, v245, v3
	v_mul_f32_e32 v246, v246, v4
	v_mul_f32_e32 v247, v247, v5
	v_cvt_pk_bf16_f32 v198, v244, v245
	v_cvt_pk_bf16_f32 v199, v246, v247
	s_waitcnt vmcnt(3)
	v_lshlrev_b32_e32 v2, 16, v200
	v_and_b32_e32 v3, 0xffff0000, v200
	v_lshlrev_b32_e32 v4, 16, v201
	v_and_b32_e32 v5, 0xffff0000, v201
	v_mul_f32_e32 v96, v96, v2
	v_mul_f32_e32 v97, v97, v3
	v_mul_f32_e32 v98, v98, v4
	v_mul_f32_e32 v99, v99, v5
	v_cvt_pk_bf16_f32 v200, v96, v97
	v_cvt_pk_bf16_f32 v201, v98, v99
	s_waitcnt vmcnt(2)
	v_lshlrev_b32_e32 v2, 16, v202
	v_and_b32_e32 v3, 0xffff0000, v202
	v_lshlrev_b32_e32 v4, 16, v203
	v_and_b32_e32 v5, 0xffff0000, v203
	v_mul_f32_e32 v100, v100, v2
	v_mul_f32_e32 v101, v101, v3
	v_mul_f32_e32 v102, v102, v4
	v_mul_f32_e32 v103, v103, v5
	v_cvt_pk_bf16_f32 v202, v100, v101
	v_cvt_pk_bf16_f32 v203, v102, v103
	s_waitcnt vmcnt(1)
	v_lshlrev_b32_e32 v2, 16, v216
	v_and_b32_e32 v3, 0xffff0000, v216
	v_lshlrev_b32_e32 v4, 16, v217
	v_and_b32_e32 v5, 0xffff0000, v217
	v_mul_f32_e32 v104, v104, v2
	v_mul_f32_e32 v105, v105, v3
	v_mul_f32_e32 v106, v106, v4
	v_mul_f32_e32 v107, v107, v5
	v_cvt_pk_bf16_f32 v216, v104, v105
	v_cvt_pk_bf16_f32 v217, v106, v107
	s_waitcnt vmcnt(0)
	v_lshlrev_b32_e32 v2, 16, v248
	v_and_b32_e32 v3, 0xffff0000, v248
	v_lshlrev_b32_e32 v4, 16, v249
	v_and_b32_e32 v5, 0xffff0000, v249
	v_mul_f32_e32 v108, v108, v2
	v_mul_f32_e32 v109, v109, v3
	v_mul_f32_e32 v110, v110, v4
	v_mul_f32_e32 v111, v111, v5
	v_cvt_pk_bf16_f32 v248, v108, v109
	v_cvt_pk_bf16_f32 v249, v110, v111
	global_store_dwordx2 v212, v[190:191], s[52:53] offset:0
	global_store_dwordx2 v212, v[192:193], s[52:53] offset:16
	global_store_dwordx2 v212, v[194:195], s[52:53] offset:32
	global_store_dwordx2 v212, v[198:199], s[52:53] offset:48
	global_store_dwordx2 v212, v[200:201], s[52:53] offset:64
	global_store_dwordx2 v212, v[202:203], s[52:53] offset:80
	global_store_dwordx2 v212, v[216:217], s[52:53] offset:96
	global_store_dwordx2 v212, v[248:249], s[52:53] offset:112
	s_branch .LBB0_470
.Lat3_rare_a1:
	s_nop 15
	v_max_f32_e32 v2, 0, v14
	v_sub_f32_e32 v0, 0, v2
	v_exp_f32_e32 v0, v0
	v_sub_f32_e32 v80, v80, v2
	v_sub_f32_e32 v81, v81, v2
	v_sub_f32_e32 v82, v82, v2
	v_sub_f32_e32 v83, v83, v2
	v_sub_f32_e32 v84, v84, v2
	v_sub_f32_e32 v85, v85, v2
	v_sub_f32_e32 v86, v86, v2
	v_sub_f32_e32 v87, v87, v2
	v_sub_f32_e32 v88, v88, v2
	v_sub_f32_e32 v89, v89, v2
	v_sub_f32_e32 v90, v90, v2
	v_sub_f32_e32 v91, v91, v2
	v_sub_f32_e32 v92, v92, v2
	v_sub_f32_e32 v93, v93, v2
	v_sub_f32_e32 v94, v94, v2
	v_sub_f32_e32 v95, v95, v2
	v_sub_f32_e32 v232, v232, v2
	v_sub_f32_e32 v233, v233, v2
	v_sub_f32_e32 v234, v234, v2
	v_sub_f32_e32 v235, v235, v2
	v_sub_f32_e32 v236, v236, v2
	v_sub_f32_e32 v237, v237, v2
	v_sub_f32_e32 v238, v238, v2
	v_sub_f32_e32 v239, v239, v2
	v_sub_f32_e32 v240, v240, v2
	v_sub_f32_e32 v241, v241, v2
	v_sub_f32_e32 v242, v242, v2
	v_sub_f32_e32 v243, v243, v2
	v_sub_f32_e32 v244, v244, v2
	v_sub_f32_e32 v245, v245, v2
	v_sub_f32_e32 v246, v246, v2
	v_sub_f32_e32 v247, v247, v2
	v_mul_f32_e32 v175, v175, v0
	v_pk_mul_f32 v[78:79], v[78:79], v[0:1] op_sel_hi:[1,0]
	v_pk_mul_f32 v[76:77], v[76:77], v[0:1] op_sel_hi:[1,0]
	v_pk_mul_f32 v[74:75], v[74:75], v[0:1] op_sel_hi:[1,0]
	v_pk_mul_f32 v[72:73], v[72:73], v[0:1] op_sel_hi:[1,0]
	v_pk_mul_f32 v[70:71], v[70:71], v[0:1] op_sel_hi:[1,0]
	v_pk_mul_f32 v[68:69], v[68:69], v[0:1] op_sel_hi:[1,0]
	v_pk_mul_f32 v[66:67], v[66:67], v[0:1] op_sel_hi:[1,0]
	v_pk_mul_f32 v[64:65], v[64:65], v[0:1] op_sel_hi:[1,0]
	v_pk_mul_f32 v[62:63], v[62:63], v[0:1] op_sel_hi:[1,0]
	v_pk_mul_f32 v[60:61], v[60:61], v[0:1] op_sel_hi:[1,0]
	v_pk_mul_f32 v[58:59], v[58:59], v[0:1] op_sel_hi:[1,0]
	v_pk_mul_f32 v[56:57], v[56:57], v[0:1] op_sel_hi:[1,0]
	v_pk_mul_f32 v[54:55], v[54:55], v[0:1] op_sel_hi:[1,0]
	v_pk_mul_f32 v[52:53], v[52:53], v[0:1] op_sel_hi:[1,0]
	v_pk_mul_f32 v[50:51], v[50:51], v[0:1] op_sel_hi:[1,0]
	v_pk_mul_f32 v[48:49], v[48:49], v[0:1] op_sel_hi:[1,0]
	v_pk_mul_f32 v[46:47], v[46:47], v[0:1] op_sel_hi:[1,0]
	v_pk_mul_f32 v[44:45], v[44:45], v[0:1] op_sel_hi:[1,0]
	v_pk_mul_f32 v[42:43], v[42:43], v[0:1] op_sel_hi:[1,0]
	v_pk_mul_f32 v[40:41], v[40:41], v[0:1] op_sel_hi:[1,0]
	v_pk_mul_f32 v[38:39], v[38:39], v[0:1] op_sel_hi:[1,0]
	v_pk_mul_f32 v[36:37], v[36:37], v[0:1] op_sel_hi:[1,0]
	v_pk_mul_f32 v[34:35], v[34:35], v[0:1] op_sel_hi:[1,0]
	v_pk_mul_f32 v[32:33], v[32:33], v[0:1] op_sel_hi:[1,0]
	v_pk_mul_f32 v[30:31], v[30:31], v[0:1] op_sel_hi:[1,0]
	v_pk_mul_f32 v[28:29], v[28:29], v[0:1] op_sel_hi:[1,0]
	v_pk_mul_f32 v[26:27], v[26:27], v[0:1] op_sel_hi:[1,0]
	v_pk_mul_f32 v[24:25], v[24:25], v[0:1] op_sel_hi:[1,0]
	v_pk_mul_f32 v[22:23], v[22:23], v[0:1] op_sel_hi:[1,0]
	v_pk_mul_f32 v[20:21], v[20:21], v[0:1] op_sel_hi:[1,0]
	v_pk_mul_f32 v[18:19], v[18:19], v[0:1] op_sel_hi:[1,0]
	v_pk_mul_f32 v[16:17], v[16:17], v[0:1] op_sel_hi:[1,0]
	s_branch .Lat3_common_a1
.Lat3_rare_a2:
	s_nop 15
	v_max_f32_e32 v2, 0, v14
	v_sub_f32_e32 v0, 0, v2
	v_exp_f32_e32 v0, v0
	v_sub_f32_e32 v96, v96, v2
	v_sub_f32_e32 v97, v97, v2
	v_sub_f32_e32 v98, v98, v2
	v_sub_f32_e32 v99, v99, v2
	v_sub_f32_e32 v100, v100, v2
	v_sub_f32_e32 v101, v101, v2
	v_sub_f32_e32 v102, v102, v2
	v_sub_f32_e32 v103, v103, v2
	v_sub_f32_e32 v104, v104, v2
	v_sub_f32_e32 v105, v105, v2
	v_sub_f32_e32 v106, v106, v2
	v_sub_f32_e32 v107, v107, v2
	v_sub_f32_e32 v108, v108, v2
	v_sub_f32_e32 v109, v109, v2
	v_sub_f32_e32 v110, v110, v2
	v_sub_f32_e32 v111, v111, v2
	v_sub_f32_e32 v232, v232, v2
	v_sub_f32_e32 v233, v233, v2
	v_sub_f32_e32 v234, v234, v2
	v_sub_f32_e32 v235, v235, v2
	v_sub_f32_e32 v236, v236, v2
	v_sub_f32_e32 v237, v237, v2
	v_sub_f32_e32 v238, v238, v2
	v_sub_f32_e32 v239, v239, v2
	v_sub_f32_e32 v240, v240, v2
	v_sub_f32_e32 v241, v241, v2
	v_sub_f32_e32 v242, v242, v2
	v_sub_f32_e32 v243, v243, v2
	v_sub_f32_e32 v244, v244, v2
	v_sub_f32_e32 v245, v245, v2
	v_sub_f32_e32 v246, v246, v2
	v_sub_f32_e32 v247, v247, v2
	v_mul_f32_e32 v175, v175, v0
	v_pk_mul_f32 v[78:79], v[78:79], v[0:1] op_sel_hi:[1,0]
	v_pk_mul_f32 v[76:77], v[76:77], v[0:1] op_sel_hi:[1,0]
	v_pk_mul_f32 v[74:75], v[74:75], v[0:1] op_sel_hi:[1,0]
	v_pk_mul_f32 v[72:73], v[72:73], v[0:1] op_sel_hi:[1,0]
	v_pk_mul_f32 v[70:71], v[70:71], v[0:1] op_sel_hi:[1,0]
	v_pk_mul_f32 v[68:69], v[68:69], v[0:1] op_sel_hi:[1,0]
	v_pk_mul_f32 v[66:67], v[66:67], v[0:1] op_sel_hi:[1,0]
	v_pk_mul_f32 v[64:65], v[64:65], v[0:1] op_sel_hi:[1,0]
	v_pk_mul_f32 v[62:63], v[62:63], v[0:1] op_sel_hi:[1,0]
	v_pk_mul_f32 v[60:61], v[60:61], v[0:1] op_sel_hi:[1,0]
	v_pk_mul_f32 v[58:59], v[58:59], v[0:1] op_sel_hi:[1,0]
	v_pk_mul_f32 v[56:57], v[56:57], v[0:1] op_sel_hi:[1,0]
	v_pk_mul_f32 v[54:55], v[54:55], v[0:1] op_sel_hi:[1,0]
	v_pk_mul_f32 v[52:53], v[52:53], v[0:1] op_sel_hi:[1,0]
	v_pk_mul_f32 v[50:51], v[50:51], v[0:1] op_sel_hi:[1,0]
	v_pk_mul_f32 v[48:49], v[48:49], v[0:1] op_sel_hi:[1,0]
	v_pk_mul_f32 v[46:47], v[46:47], v[0:1] op_sel_hi:[1,0]
	v_pk_mul_f32 v[44:45], v[44:45], v[0:1] op_sel_hi:[1,0]
	v_pk_mul_f32 v[42:43], v[42:43], v[0:1] op_sel_hi:[1,0]
	v_pk_mul_f32 v[40:41], v[40:41], v[0:1] op_sel_hi:[1,0]
	v_pk_mul_f32 v[38:39], v[38:39], v[0:1] op_sel_hi:[1,0]
	v_pk_mul_f32 v[36:37], v[36:37], v[0:1] op_sel_hi:[1,0]
	v_pk_mul_f32 v[34:35], v[34:35], v[0:1] op_sel_hi:[1,0]
	v_pk_mul_f32 v[32:33], v[32:33], v[0:1] op_sel_hi:[1,0]
	v_pk_mul_f32 v[30:31], v[30:31], v[0:1] op_sel_hi:[1,0]
	v_pk_mul_f32 v[28:29], v[28:29], v[0:1] op_sel_hi:[1,0]
	v_pk_mul_f32 v[26:27], v[26:27], v[0:1] op_sel_hi:[1,0]
	v_pk_mul_f32 v[24:25], v[24:25], v[0:1] op_sel_hi:[1,0]
	v_pk_mul_f32 v[22:23], v[22:23], v[0:1] op_sel_hi:[1,0]
	v_pk_mul_f32 v[20:21], v[20:21], v[0:1] op_sel_hi:[1,0]
	v_pk_mul_f32 v[18:19], v[18:19], v[0:1] op_sel_hi:[1,0]
	v_pk_mul_f32 v[16:17], v[16:17], v[0:1] op_sel_hi:[1,0]
	s_branch .Lat3_common_a2

	.amdhsa_kernel _Z10fwd_kernelILin1EEv6Params
		.amdhsa_group_segment_fixed_size 0
		.amdhsa_private_segment_fixed_size 0
		.amdhsa_kernarg_size 2464
		.amdhsa_user_sgpr_count 2
		.amdhsa_user_sgpr_dispatch_ptr 0
		.amdhsa_user_sgpr_queue_ptr 0
		.amdhsa_user_sgpr_kernarg_segment_ptr 1
		.amdhsa_user_sgpr_dispatch_id 0
		.amdhsa_user_sgpr_kernarg_preload_length 0
		.amdhsa_user_sgpr_kernarg_preload_offset 0
		.amdhsa_user_sgpr_private_segment_size 0
		.amdhsa_uses_dynamic_stack 0
		.amdhsa_enable_private_segment 0
		.amdhsa_system_sgpr_workgroup_id_x 1
		.amdhsa_system_sgpr_workgroup_id_y 0
		.amdhsa_system_sgpr_workgroup_id_z 0
		.amdhsa_system_sgpr_workgroup_info 0
		.amdhsa_system_vgpr_workitem_id 2
		.amdhsa_next_free_vgpr 251
		.amdhsa_next_free_sgpr 102
		.amdhsa_accum_offset 252
		.amdhsa_reserve_vcc 1
		.amdhsa_float_round_mode_32 0
		.amdhsa_float_round_mode_16_64 0
		.amdhsa_float_denorm_mode_32 3
		.amdhsa_float_denorm_mode_16_64 3
		.amdhsa_dx10_clamp 1
		.amdhsa_ieee_mode 1
		.amdhsa_fp16_overflow 0
		.amdhsa_tg_split 0
		.amdhsa_exception_fp_ieee_invalid_op 0
		.amdhsa_exception_fp_denorm_src 0
		.amdhsa_exception_fp_ieee_div_zero 0
		.amdhsa_exception_fp_ieee_overflow 0
		.amdhsa_exception_fp_ieee_underflow 0
		.amdhsa_exception_fp_ieee_inexact 0
		.amdhsa_exception_int_div_zero 0
	.end_amdhsa_kernel

amdhsa.kernels:
  - .agpr_count:     0
    .args:
      - .offset:         0
        .size:           2208
        .value_kind:     by_value
      - .offset:         2208
        .size:           4
        .value_kind:     hidden_block_count_x
      - .offset:         2212
        .size:           4
        .value_kind:     hidden_block_count_y
      - .offset:         2216
        .size:           4
        .value_kind:     hidden_block_count_z
      - .offset:         2220
        .size:           2
        .value_kind:     hidden_group_size_x
      - .offset:         2222
        .size:           2
        .value_kind:     hidden_group_size_y
      - .offset:         2224
        .size:           2
        .value_kind:     hidden_group_size_z
      - .offset:         2226
        .size:           2
        .value_kind:     hidden_remainder_x
      - .offset:         2228
        .size:           2
        .value_kind:     hidden_remainder_y
      - .offset:         2230
        .size:           2
        .value_kind:     hidden_remainder_z
      - .offset:         2248
        .size:           8
        .value_kind:     hidden_global_offset_x
      - .offset:         2256
        .size:           8
        .value_kind:     hidden_global_offset_y
      - .offset:         2264
        .size:           8
        .value_kind:     hidden_global_offset_z
      - .offset:         2272
        .size:           2
        .value_kind:     hidden_grid_dims
      - .offset:         2296
        .size:           8
        .value_kind:     hidden_multigrid_sync_arg
      - .offset:         2328
        .size:           4
        .value_kind:     hidden_dynamic_lds_size
    .group_segment_fixed_size: 0
    .kernarg_segment_align: 8
    .kernarg_segment_size: 2464
    .language:       OpenCL C
    .language_version:
      - 2
      - 0
    .max_flat_workgroup_size: 512
    .name:           _Z10fwd_kernelILin1EEv6Params
    .private_segment_fixed_size: 0
    .sgpr_count:     108
    .sgpr_spill_count: 10
    .symbol:         _Z10fwd_kernelILin1EEv6Params.kd
    .uniform_work_group_size: 1
    .uses_dynamic_stack: false
    .vgpr_count:     251
    .vgpr_spill_count: 0
    .wavefront_size: 64
